# attention: compressed branch (single-pass exact softmax, 3 barriers) and top-k (radix select) rewritten by hand
# speedup vs baseline: 1.2266x; 1.0285x over previous
.LBB0_148:
	s_or_b64 exec, exec, s[0:1]
	s_mov_b64 s[0:1], src_shared_base
	v_mov_b32_e32 v177, s1
	s_waitcnt lgkmcnt(0)
	s_barrier
	flat_load_dword v0, v[176:177] sc0 sc1
	s_waitcnt vmcnt(0)
	s_mov_b64 s[0:1], -1
	s_waitcnt lgkmcnt(0)
	v_readfirstlane_b32 s2, v0
	s_cmpk_gt_i32 s2, 0x3ff
	s_cbranch_scc1 .LBB0_143
	v_lshrrev_b32_e32 v189, 6, v163
	v_and_b32_e32 v212, 15, v163
	v_bfe_u32 v213, v163, 4, 2
	v_readfirstlane_b32 s7, v189
	s_lshr_b32 s3, s2, 3
	s_sub_i32 s3, 0x7f, s3
	s_and_b32 s6, s2, 7
	s_lshr_b32 s4, s3, 1
	s_and_b32 s5, s3, 1
	s_lshl_b32 s5, s5, 5
	s_lshr_b32 s28, s6, 1
	s_lshl_b32 s9, s28, 12
	s_lshl_b32 s29, s3, 5
	s_add_i32 s9, s9, s29
	s_and_b32 s8, s6, 1
	s_lshl_b32 s8, s8, 2
	s_add_i32 s8, s8, s7
	s_lshl_b32 s18, s7, 10
	s_add_i32 s19, s3, 64
	s_lshr_b32 s19, s19, 6
	v_readlane_b32 s52, v236, 41
	v_readlane_b32 s53, v236, 42
	s_lshl_b32 s28, s8, 7
	s_add_u32 s52, s52, s28
	s_addc_u32 s53, s53, 0
	v_add_u32_e32 v190, s9, v212
	v_lshlrev_b32_e32 v191, 10, v190
	v_lshl_add_u32 v191, v213, 4, v191
	v_add_u32_e32 v206, 0x4000, v191
	global_load_dwordx4 v[98:101], v191, s[52:53]
	global_load_dwordx4 v[102:105], v191, s[52:53] offset:64
	global_load_dwordx4 v[106:109], v206, s[52:53]
	global_load_dwordx4 v[110:113], v206, s[52:53] offset:64
	v_readlane_b32 s36, v236, 31
	v_readlane_b32 s37, v236, 32
	s_mul_i32 s28, s8, 6
	s_add_i32 s28, s28, 0x3200
	s_add_u32 s36, s36, s28
	s_addc_u32 s37, s37, 0
	v_mul_u32_u24_e32 v207, 0x3300, v190
	v_add_u32_e32 v208, 0x33000, v207
	global_load_ushort v220, v207, s[36:37]
	global_load_ushort v221, v208, s[36:37]
	v_readlane_b32 s10, v237, 57
	v_readlane_b32 s11, v237, 58
	v_readlane_b32 s12, v237, 59
	v_readlane_b32 s13, v237, 60
	s_lshl_b32 s28, s6, 14
	s_add_u32 s10, s10, s28
	s_addc_u32 s11, s11, 0
	s_add_u32 s12, s12, s28
	s_addc_u32 s13, s13, 0
	v_lshrrev_b32_e32 v206, 3, v163
	v_and_b32_e32 v207, 7, v163
	v_bfe_u32 v208, v163, 4, 3
	v_xor_b32_e32 v207, v207, v208
	v_lshlrev_b32_e32 v207, 4, v207
	v_lshl_add_u32 v150, v206, 7, v207
	v_add_u32_e32 v151, 0x1000, v150
	v_lshl_add_u32 v228, v206, 8, v207
	v_add_u32_e32 v229, 0x2000, v228
	s_mov_b32 s14, s10
	s_mov_b32 s15, s11
	s_mov_b32 s16, s12
	s_mov_b32 s17, s13
	s_mov_b32 m0, s18
	s_nop 0
	global_load_lds_dwordx4 v150, s[14:15]
	s_add_u32 m0, s18, 0x1000
	s_nop 0
	global_load_lds_dwordx4 v151, s[14:15]
	s_add_u32 m0, s18, 0x2000
	s_nop 0
	global_load_lds_dwordx4 v228, s[16:17]
	s_add_u32 m0, s18, 0x3000
	s_nop 0
	global_load_lds_dwordx4 v229, s[16:17]
	s_cmp_eq_u32 s19, 2
	s_cbranch_scc0 .La3_dma1x
	s_add_u32 s14, s10, 0x2000
	s_addc_u32 s15, s11, 0
	s_add_u32 s16, s12, 0x80
	s_addc_u32 s17, s13, 0
	s_add_u32 m0, s18, 0x8000
	s_nop 0
	global_load_lds_dwordx4 v150, s[14:15]
	s_add_u32 m0, s18, 0x9000
	s_nop 0
	global_load_lds_dwordx4 v151, s[14:15]
	s_add_u32 m0, s18, 0xa000
	s_nop 0
	global_load_lds_dwordx4 v228, s[16:17]
	s_add_u32 m0, s18, 0xb000
	s_nop 0
	global_load_lds_dwordx4 v229, s[16:17]
.La3_dma1x:
	v_bfe_u32 v190, v163, 1, 3
	v_and_b32_e32 v206, 3, v190
	v_xor_b32_e32 v206, v206, v213
	v_lshlrev_b32_e32 v206, 4, v206
	v_lshrrev_b32_e32 v207, 2, v190
	v_lshl_or_b32 v206, v207, 6, v206
	v_lshl_or_b32 v222, v212, 7, v206
	v_xor_b32_e32 v223, 64, v222
	v_lshrrev_b32_e32 v206, 1, v213
	v_and_b32_e32 v207, 1, v190
	v_xor_b32_e32 v206, v206, v207
	v_and_b32_e32 v207, 6, v190
	v_or_b32_e32 v206, v206, v207
	v_lshlrev_b32_e32 v206, 4, v206
	v_and_b32_e32 v207, 1, v213
	v_lshl_or_b32 v206, v207, 3, v206
	v_lshl_or_b32 v224, v212, 7, v206
	v_add_u32_e32 v224, 0x2000, v224
	v_xor_b32_e32 v225, 32, v224
	v_xor_b32_e32 v226, 64, v224
	v_xor_b32_e32 v227, 32, v226
	v_and_b32_e32 v214, 63, v163
	v_xor_b32_e32 v214, 32, v214
	v_lshlrev_b32_e32 v214, 2, v214
	v_lshlrev_b32_e32 v206, 2, v213
	v_sub_u32_e32 v230, s3, v206
	v_cmp_eq_u32_e32 vcc, 15, v212
	s_nop 1
	v_addc_co_u32_e32 v231, vcc, 0, v230, vcc
	s_and_b32 s28, s7, 1
	s_lshl_b32 s28, s28, 13
	s_lshr_b32 s29, s7, 1
	s_lshl_b32 s29, s29, 15
	s_add_i32 s28, s28, s29
	s_add_i32 s28, s28, 0x4000
	v_lshlrev_b32_e32 v232, 8, v213
	v_lshl_add_u32 v232, v212, 2, v232
	v_add_u32_e32 v232, s28, v232
	v_mov_b32_e32 v2, 0
	v_mov_b32_e32 v3, 0
	v_mov_b32_e32 v4, 0
	v_mov_b32_e32 v5, 0
	v_mov_b32_e32 v6, 0
	v_mov_b32_e32 v7, 0
	v_mov_b32_e32 v8, 0
	v_mov_b32_e32 v9, 0
	v_mov_b32_e32 v10, 0
	v_mov_b32_e32 v11, 0
	v_mov_b32_e32 v12, 0
	v_mov_b32_e32 v13, 0
	v_mov_b32_e32 v14, 0
	v_mov_b32_e32 v15, 0
	v_mov_b32_e32 v16, 0
	v_mov_b32_e32 v17, 0
	v_mov_b32_e32 v18, 0
	v_mov_b32_e32 v19, 0
	v_mov_b32_e32 v20, 0
	v_mov_b32_e32 v21, 0
	v_mov_b32_e32 v22, 0
	v_mov_b32_e32 v23, 0
	v_mov_b32_e32 v24, 0
	v_mov_b32_e32 v25, 0
	v_mov_b32_e32 v26, 0
	v_mov_b32_e32 v27, 0
	v_mov_b32_e32 v28, 0
	v_mov_b32_e32 v29, 0
	v_mov_b32_e32 v30, 0
	v_mov_b32_e32 v31, 0
	v_mov_b32_e32 v32, 0
	v_mov_b32_e32 v33, 0
	s_waitcnt vmcnt(0)
	s_barrier
	ds_read_b128 v[148:151], v222
	ds_read_b128 v[152:155], v222 offset:2048
	ds_read_b128 v[156:159], v222 offset:4096
	ds_read_b128 v[184:187], v222 offset:6144
	s_waitcnt lgkmcnt(3)
	v_mfma_f32_16x16x32_bf16 v[34:37], v[148:151], v[98:101], 0
	v_mfma_f32_16x16x32_bf16 v[38:41], v[148:151], v[106:109], 0
	s_waitcnt lgkmcnt(2)
	v_mfma_f32_16x16x32_bf16 v[42:45], v[152:155], v[98:101], 0
	v_mfma_f32_16x16x32_bf16 v[46:49], v[152:155], v[106:109], 0
	s_waitcnt lgkmcnt(1)
	v_mfma_f32_16x16x32_bf16 v[50:53], v[156:159], v[98:101], 0
	v_mfma_f32_16x16x32_bf16 v[54:57], v[156:159], v[106:109], 0
	s_waitcnt lgkmcnt(0)
	v_mfma_f32_16x16x32_bf16 v[58:61], v[184:187], v[98:101], 0
	v_mfma_f32_16x16x32_bf16 v[62:65], v[184:187], v[106:109], 0
	ds_read_b128 v[148:151], v223
	ds_read_b128 v[152:155], v223 offset:2048
	ds_read_b128 v[156:159], v223 offset:4096
	ds_read_b128 v[184:187], v223 offset:6144
	s_waitcnt lgkmcnt(3)
	v_mfma_f32_16x16x32_bf16 v[34:37], v[148:151], v[102:105], v[34:37]
	v_mfma_f32_16x16x32_bf16 v[38:41], v[148:151], v[110:113], v[38:41]
	s_waitcnt lgkmcnt(2)
	v_mfma_f32_16x16x32_bf16 v[42:45], v[152:155], v[102:105], v[42:45]
	v_mfma_f32_16x16x32_bf16 v[46:49], v[152:155], v[110:113], v[46:49]
	s_waitcnt lgkmcnt(1)
	v_mfma_f32_16x16x32_bf16 v[50:53], v[156:159], v[102:105], v[50:53]
	v_mfma_f32_16x16x32_bf16 v[54:57], v[156:159], v[110:113], v[54:57]
	s_waitcnt lgkmcnt(0)
	v_mfma_f32_16x16x32_bf16 v[58:61], v[184:187], v[102:105], v[58:61]
	v_mfma_f32_16x16x32_bf16 v[62:65], v[184:187], v[110:113], v[62:65]
	s_cmp_eq_u32 s19, 2
	s_cbranch_scc0 .La3_qk1x
	ds_read_b128 v[148:151], v222 offset:32768
	ds_read_b128 v[152:155], v222 offset:34816
	ds_read_b128 v[156:159], v222 offset:36864
	ds_read_b128 v[184:187], v222 offset:38912
	s_waitcnt lgkmcnt(3)
	v_mfma_f32_16x16x32_bf16 v[66:69], v[148:151], v[98:101], 0
	v_mfma_f32_16x16x32_bf16 v[70:73], v[148:151], v[106:109], 0
	s_waitcnt lgkmcnt(2)
	v_mfma_f32_16x16x32_bf16 v[74:77], v[152:155], v[98:101], 0
	v_mfma_f32_16x16x32_bf16 v[78:81], v[152:155], v[106:109], 0
	s_waitcnt lgkmcnt(1)
	v_mfma_f32_16x16x32_bf16 v[82:85], v[156:159], v[98:101], 0
	v_mfma_f32_16x16x32_bf16 v[86:89], v[156:159], v[106:109], 0
	s_waitcnt lgkmcnt(0)
	v_mfma_f32_16x16x32_bf16 v[90:93], v[184:187], v[98:101], 0
	v_mfma_f32_16x16x32_bf16 v[94:97], v[184:187], v[106:109], 0
	ds_read_b128 v[148:151], v223 offset:32768
	ds_read_b128 v[152:155], v223 offset:34816
	ds_read_b128 v[156:159], v223 offset:36864
	ds_read_b128 v[184:187], v223 offset:38912
	s_waitcnt lgkmcnt(3)
	v_mfma_f32_16x16x32_bf16 v[66:69], v[148:151], v[102:105], v[66:69]
	v_mfma_f32_16x16x32_bf16 v[70:73], v[148:151], v[110:113], v[70:73]
	s_waitcnt lgkmcnt(2)
	v_mfma_f32_16x16x32_bf16 v[74:77], v[152:155], v[102:105], v[74:77]
	v_mfma_f32_16x16x32_bf16 v[78:81], v[152:155], v[110:113], v[78:81]
	s_waitcnt lgkmcnt(1)
	v_mfma_f32_16x16x32_bf16 v[82:85], v[156:159], v[102:105], v[82:85]
	v_mfma_f32_16x16x32_bf16 v[86:89], v[156:159], v[110:113], v[86:89]
	s_waitcnt lgkmcnt(0)
	v_mfma_f32_16x16x32_bf16 v[90:93], v[184:187], v[102:105], v[90:93]
	v_mfma_f32_16x16x32_bf16 v[94:97], v[184:187], v[110:113], v[94:97]
.La3_qk1x:
	s_nop 7
	s_nop 1
	v_cmp_lt_i32_e64 s[44:45], 0, v230
	s_nop 1
	v_cndmask_b32_e64 v34, v199, v34, s[44:45]
	v_cmp_lt_i32_e64 s[46:47], 1, v230
	s_nop 1
	v_cndmask_b32_e64 v35, v199, v35, s[46:47]
	v_cmp_lt_i32_e64 s[48:49], 2, v230
	s_nop 1
	v_cndmask_b32_e64 v36, v199, v36, s[48:49]
	v_cmp_lt_i32_e64 s[50:51], 3, v230
	s_nop 1
	v_cndmask_b32_e64 v37, v199, v37, s[50:51]
	v_cmp_lt_i32_e64 s[44:45], 16, v230
	s_nop 1
	v_cndmask_b32_e64 v42, v199, v42, s[44:45]
	v_cmp_lt_i32_e64 s[46:47], 17, v230
	s_nop 1
	v_cndmask_b32_e64 v43, v199, v43, s[46:47]
	v_cmp_lt_i32_e64 s[48:49], 18, v230
	s_nop 1
	v_cndmask_b32_e64 v44, v199, v44, s[48:49]
	v_cmp_lt_i32_e64 s[50:51], 19, v230
	s_nop 1
	v_cndmask_b32_e64 v45, v199, v45, s[50:51]
	v_cmp_lt_i32_e64 s[44:45], 32, v230
	s_nop 1
	v_cndmask_b32_e64 v50, v199, v50, s[44:45]
	v_cmp_lt_i32_e64 s[46:47], 33, v230
	s_nop 1
	v_cndmask_b32_e64 v51, v199, v51, s[46:47]
	v_cmp_lt_i32_e64 s[48:49], 34, v230
	s_nop 1
	v_cndmask_b32_e64 v52, v199, v52, s[48:49]
	v_cmp_lt_i32_e64 s[50:51], 35, v230
	s_nop 1
	v_cndmask_b32_e64 v53, v199, v53, s[50:51]
	v_cmp_lt_i32_e64 s[44:45], 48, v230
	s_nop 1
	v_cndmask_b32_e64 v58, v199, v58, s[44:45]
	v_cmp_lt_i32_e64 s[46:47], 49, v230
	s_nop 1
	v_cndmask_b32_e64 v59, v199, v59, s[46:47]
	v_cmp_lt_i32_e64 s[48:49], 50, v230
	s_nop 1
	v_cndmask_b32_e64 v60, v199, v60, s[48:49]
	v_cmp_lt_i32_e64 s[50:51], 51, v230
	s_nop 1
	v_cndmask_b32_e64 v61, v199, v61, s[50:51]
	v_cmp_lt_i32_e64 s[44:45], 0, v231
	s_nop 1
	v_cndmask_b32_e64 v38, v199, v38, s[44:45]
	v_cmp_lt_i32_e64 s[46:47], 1, v231
	s_nop 1
	v_cndmask_b32_e64 v39, v199, v39, s[46:47]
	v_cmp_lt_i32_e64 s[48:49], 2, v231
	s_nop 1
	v_cndmask_b32_e64 v40, v199, v40, s[48:49]
	v_cmp_lt_i32_e64 s[50:51], 3, v231
	s_nop 1
	v_cndmask_b32_e64 v41, v199, v41, s[50:51]
	v_cmp_lt_i32_e64 s[44:45], 16, v231
	s_nop 1
	v_cndmask_b32_e64 v46, v199, v46, s[44:45]
	v_cmp_lt_i32_e64 s[46:47], 17, v231
	s_nop 1
	v_cndmask_b32_e64 v47, v199, v47, s[46:47]
	v_cmp_lt_i32_e64 s[48:49], 18, v231
	s_nop 1
	v_cndmask_b32_e64 v48, v199, v48, s[48:49]
	v_cmp_lt_i32_e64 s[50:51], 19, v231
	s_nop 1
	v_cndmask_b32_e64 v49, v199, v49, s[50:51]
	v_cmp_lt_i32_e64 s[44:45], 32, v231
	s_nop 1
	v_cndmask_b32_e64 v54, v199, v54, s[44:45]
	v_cmp_lt_i32_e64 s[46:47], 33, v231
	s_nop 1
	v_cndmask_b32_e64 v55, v199, v55, s[46:47]
	v_cmp_lt_i32_e64 s[48:49], 34, v231
	s_nop 1
	v_cndmask_b32_e64 v56, v199, v56, s[48:49]
	v_cmp_lt_i32_e64 s[50:51], 35, v231
	s_nop 1
	v_cndmask_b32_e64 v57, v199, v57, s[50:51]
	v_cmp_lt_i32_e64 s[44:45], 48, v231
	s_nop 1
	v_cndmask_b32_e64 v62, v199, v62, s[44:45]
	v_cmp_lt_i32_e64 s[46:47], 49, v231
	s_nop 1
	v_cndmask_b32_e64 v63, v199, v63, s[46:47]
	v_cmp_lt_i32_e64 s[48:49], 50, v231
	s_nop 1
	v_cndmask_b32_e64 v64, v199, v64, s[48:49]
	v_cmp_lt_i32_e64 s[50:51], 51, v231
	s_nop 1
	v_cndmask_b32_e64 v65, v199, v65, s[50:51]
	v_max3_f32 v215, v34, v35, v36
	v_max3_f32 v215, v215, v37, v42
	v_max3_f32 v215, v215, v43, v44
	v_max3_f32 v215, v215, v45, v50
	v_max3_f32 v215, v215, v51, v52
	v_max3_f32 v215, v215, v53, v58
	v_max3_f32 v215, v215, v59, v60
	v_max_f32_e32 v215, v215, v61
	v_max3_f32 v216, v38, v39, v40
	v_max3_f32 v216, v216, v41, v46
	v_max3_f32 v216, v216, v47, v48
	v_max3_f32 v216, v216, v49, v54
	v_max3_f32 v216, v216, v55, v56
	v_max3_f32 v216, v216, v57, v62
	v_max3_f32 v216, v216, v63, v64
	v_max_f32_e32 v216, v216, v65
	s_cmp_eq_u32 s19, 2
	s_cbranch_scc0 .La3_m1x
	v_cmp_lt_i32_e64 s[44:45], 64, v230
	s_nop 1
	v_cndmask_b32_e64 v66, v199, v66, s[44:45]
	s_movk_i32 s30, 65
	v_cmp_lt_i32_e64 s[46:47], s30, v230
	s_nop 1
	v_cndmask_b32_e64 v67, v199, v67, s[46:47]
	s_movk_i32 s30, 66
	v_cmp_lt_i32_e64 s[48:49], s30, v230
	s_nop 1
	v_cndmask_b32_e64 v68, v199, v68, s[48:49]
	s_movk_i32 s30, 67
	v_cmp_lt_i32_e64 s[50:51], s30, v230
	s_nop 1
	v_cndmask_b32_e64 v69, v199, v69, s[50:51]
	s_movk_i32 s30, 80
	v_cmp_lt_i32_e64 s[44:45], s30, v230
	s_nop 1
	v_cndmask_b32_e64 v74, v199, v74, s[44:45]
	s_movk_i32 s30, 81
	v_cmp_lt_i32_e64 s[46:47], s30, v230
	s_nop 1
	v_cndmask_b32_e64 v75, v199, v75, s[46:47]
	s_movk_i32 s30, 82
	v_cmp_lt_i32_e64 s[48:49], s30, v230
	s_nop 1
	v_cndmask_b32_e64 v76, v199, v76, s[48:49]
	s_movk_i32 s30, 83
	v_cmp_lt_i32_e64 s[50:51], s30, v230
	s_nop 1
	v_cndmask_b32_e64 v77, v199, v77, s[50:51]
	s_movk_i32 s30, 96
	v_cmp_lt_i32_e64 s[44:45], s30, v230
	s_nop 1
	v_cndmask_b32_e64 v82, v199, v82, s[44:45]
	s_movk_i32 s30, 97
	v_cmp_lt_i32_e64 s[46:47], s30, v230
	s_nop 1
	v_cndmask_b32_e64 v83, v199, v83, s[46:47]
	s_movk_i32 s30, 98
	v_cmp_lt_i32_e64 s[48:49], s30, v230
	s_nop 1
	v_cndmask_b32_e64 v84, v199, v84, s[48:49]
	s_movk_i32 s30, 99
	v_cmp_lt_i32_e64 s[50:51], s30, v230
	s_nop 1
	v_cndmask_b32_e64 v85, v199, v85, s[50:51]
	s_movk_i32 s30, 112
	v_cmp_lt_i32_e64 s[44:45], s30, v230
	s_nop 1
	v_cndmask_b32_e64 v90, v199, v90, s[44:45]
	s_movk_i32 s30, 113
	v_cmp_lt_i32_e64 s[46:47], s30, v230
	s_nop 1
	v_cndmask_b32_e64 v91, v199, v91, s[46:47]
	s_movk_i32 s30, 114
	v_cmp_lt_i32_e64 s[48:49], s30, v230
	s_nop 1
	v_cndmask_b32_e64 v92, v199, v92, s[48:49]
	s_movk_i32 s30, 115
	v_cmp_lt_i32_e64 s[50:51], s30, v230
	s_nop 1
	v_cndmask_b32_e64 v93, v199, v93, s[50:51]
	v_cmp_lt_i32_e64 s[44:45], 64, v231
	s_nop 1
	v_cndmask_b32_e64 v70, v199, v70, s[44:45]
	s_movk_i32 s30, 65
	v_cmp_lt_i32_e64 s[46:47], s30, v231
	s_nop 1
	v_cndmask_b32_e64 v71, v199, v71, s[46:47]
	s_movk_i32 s30, 66
	v_cmp_lt_i32_e64 s[48:49], s30, v231
	s_nop 1
	v_cndmask_b32_e64 v72, v199, v72, s[48:49]
	s_movk_i32 s30, 67
	v_cmp_lt_i32_e64 s[50:51], s30, v231
	s_nop 1
	v_cndmask_b32_e64 v73, v199, v73, s[50:51]
	s_movk_i32 s30, 80
	v_cmp_lt_i32_e64 s[44:45], s30, v231
	s_nop 1
	v_cndmask_b32_e64 v78, v199, v78, s[44:45]
	s_movk_i32 s30, 81
	v_cmp_lt_i32_e64 s[46:47], s30, v231
	s_nop 1
	v_cndmask_b32_e64 v79, v199, v79, s[46:47]
	s_movk_i32 s30, 82
	v_cmp_lt_i32_e64 s[48:49], s30, v231
	s_nop 1
	v_cndmask_b32_e64 v80, v199, v80, s[48:49]
	s_movk_i32 s30, 83
	v_cmp_lt_i32_e64 s[50:51], s30, v231
	s_nop 1
	v_cndmask_b32_e64 v81, v199, v81, s[50:51]
	s_movk_i32 s30, 96
	v_cmp_lt_i32_e64 s[44:45], s30, v231
	s_nop 1
	v_cndmask_b32_e64 v86, v199, v86, s[44:45]
	s_movk_i32 s30, 97
	v_cmp_lt_i32_e64 s[46:47], s30, v231
	s_nop 1
	v_cndmask_b32_e64 v87, v199, v87, s[46:47]
	s_movk_i32 s30, 98
	v_cmp_lt_i32_e64 s[48:49], s30, v231
	s_nop 1
	v_cndmask_b32_e64 v88, v199, v88, s[48:49]
	s_movk_i32 s30, 99
	v_cmp_lt_i32_e64 s[50:51], s30, v231
	s_nop 1
	v_cndmask_b32_e64 v89, v199, v89, s[50:51]
	s_movk_i32 s30, 112
	v_cmp_lt_i32_e64 s[44:45], s30, v231
	s_nop 1
	v_cndmask_b32_e64 v94, v199, v94, s[44:45]
	s_movk_i32 s30, 113
	v_cmp_lt_i32_e64 s[46:47], s30, v231
	s_nop 1
	v_cndmask_b32_e64 v95, v199, v95, s[46:47]
	s_movk_i32 s30, 114
	v_cmp_lt_i32_e64 s[48:49], s30, v231
	s_nop 1
	v_cndmask_b32_e64 v96, v199, v96, s[48:49]
	s_movk_i32 s30, 115
	v_cmp_lt_i32_e64 s[50:51], s30, v231
	s_nop 1
	v_cndmask_b32_e64 v97, v199, v97, s[50:51]
	v_max3_f32 v215, v215, v66, v67
	v_max3_f32 v215, v215, v68, v69
	v_max3_f32 v215, v215, v74, v75
	v_max3_f32 v215, v215, v76, v77
	v_max3_f32 v215, v215, v82, v83
	v_max3_f32 v215, v215, v84, v85
	v_max3_f32 v215, v215, v90, v91
	v_max3_f32 v215, v215, v92, v93
	v_max3_f32 v216, v216, v70, v71
	v_max3_f32 v216, v216, v72, v73
	v_max3_f32 v216, v216, v78, v79
	v_max3_f32 v216, v216, v80, v81
	v_max3_f32 v216, v216, v86, v87
	v_max3_f32 v216, v216, v88, v89
	v_max3_f32 v216, v216, v94, v95
	v_max3_f32 v216, v216, v96, v97
.La3_m1x:
	ds_swizzle_b32 v188, v215 offset:0x401f
	s_waitcnt lgkmcnt(0)
	v_max_f32_e32 v215, v215, v188
	s_nop 0
	ds_bpermute_b32 v188, v214, v215
	s_waitcnt lgkmcnt(0)
	v_max_f32_e32 v215, v215, v188
	v_max_f32_e32 v215, 0xee013f39, v215
	ds_swizzle_b32 v188, v216 offset:0x401f
	s_waitcnt lgkmcnt(0)
	v_max_f32_e32 v216, v216, v188
	s_nop 0
	ds_bpermute_b32 v188, v214, v216
	s_waitcnt lgkmcnt(0)
	v_max_f32_e32 v216, v216, v188
	v_max_f32_e32 v216, 0xee013f39, v216
	v_sub_f32_e32 v34, v34, v215
	v_sub_f32_e32 v35, v35, v215
	v_sub_f32_e32 v36, v36, v215
	v_sub_f32_e32 v37, v37, v215
	v_sub_f32_e32 v42, v42, v215
	v_sub_f32_e32 v43, v43, v215
	v_sub_f32_e32 v44, v44, v215
	v_sub_f32_e32 v45, v45, v215
	v_sub_f32_e32 v50, v50, v215
	v_sub_f32_e32 v51, v51, v215
	v_sub_f32_e32 v52, v52, v215
	v_sub_f32_e32 v53, v53, v215
	v_sub_f32_e32 v58, v58, v215
	v_sub_f32_e32 v59, v59, v215
	v_sub_f32_e32 v60, v60, v215
	v_sub_f32_e32 v61, v61, v215
	v_exp_f32_e32 v34, v34
	v_exp_f32_e32 v35, v35
	v_exp_f32_e32 v36, v36
	v_exp_f32_e32 v37, v37
	v_exp_f32_e32 v42, v42
	v_exp_f32_e32 v43, v43
	v_exp_f32_e32 v44, v44
	v_exp_f32_e32 v45, v45
	v_exp_f32_e32 v50, v50
	v_exp_f32_e32 v51, v51
	v_exp_f32_e32 v52, v52
	v_exp_f32_e32 v53, v53
	v_exp_f32_e32 v58, v58
	v_exp_f32_e32 v59, v59
	v_exp_f32_e32 v60, v60
	v_exp_f32_e32 v61, v61
	v_add_f32_e32 v217, v34, v35
	v_add_f32_e32 v217, v217, v36
	v_add_f32_e32 v217, v217, v37
	v_add_f32_e32 v217, v217, v42
	v_add_f32_e32 v217, v217, v43
	v_add_f32_e32 v217, v217, v44
	v_add_f32_e32 v217, v217, v45
	v_add_f32_e32 v217, v217, v50
	v_add_f32_e32 v217, v217, v51
	v_add_f32_e32 v217, v217, v52
	v_add_f32_e32 v217, v217, v53
	v_add_f32_e32 v217, v217, v58
	v_add_f32_e32 v217, v217, v59
	v_add_f32_e32 v217, v217, v60
	v_add_f32_e32 v217, v217, v61
	v_sub_f32_e32 v38, v38, v216
	v_sub_f32_e32 v39, v39, v216
	v_sub_f32_e32 v40, v40, v216
	v_sub_f32_e32 v41, v41, v216
	v_sub_f32_e32 v46, v46, v216
	v_sub_f32_e32 v47, v47, v216
	v_sub_f32_e32 v48, v48, v216
	v_sub_f32_e32 v49, v49, v216
	v_sub_f32_e32 v54, v54, v216
	v_sub_f32_e32 v55, v55, v216
	v_sub_f32_e32 v56, v56, v216
	v_sub_f32_e32 v57, v57, v216
	v_sub_f32_e32 v62, v62, v216
	v_sub_f32_e32 v63, v63, v216
	v_sub_f32_e32 v64, v64, v216
	v_sub_f32_e32 v65, v65, v216
	v_exp_f32_e32 v38, v38
	v_exp_f32_e32 v39, v39
	v_exp_f32_e32 v40, v40
	v_exp_f32_e32 v41, v41
	v_exp_f32_e32 v46, v46
	v_exp_f32_e32 v47, v47
	v_exp_f32_e32 v48, v48
	v_exp_f32_e32 v49, v49
	v_exp_f32_e32 v54, v54
	v_exp_f32_e32 v55, v55
	v_exp_f32_e32 v56, v56
	v_exp_f32_e32 v57, v57
	v_exp_f32_e32 v62, v62
	v_exp_f32_e32 v63, v63
	v_exp_f32_e32 v64, v64
	v_exp_f32_e32 v65, v65
	v_add_f32_e32 v218, v38, v39
	v_add_f32_e32 v218, v218, v40
	v_add_f32_e32 v218, v218, v41
	v_add_f32_e32 v218, v218, v46
	v_add_f32_e32 v218, v218, v47
	v_add_f32_e32 v218, v218, v48
	v_add_f32_e32 v218, v218, v49
	v_add_f32_e32 v218, v218, v54
	v_add_f32_e32 v218, v218, v55
	v_add_f32_e32 v218, v218, v56
	v_add_f32_e32 v218, v218, v57
	v_add_f32_e32 v218, v218, v62
	v_add_f32_e32 v218, v218, v63
	v_add_f32_e32 v218, v218, v64
	v_add_f32_e32 v218, v218, v65
	s_cmp_eq_u32 s19, 2
	s_cbranch_scc0 .La3_e1x
	v_sub_f32_e32 v66, v66, v215
	v_sub_f32_e32 v67, v67, v215
	v_sub_f32_e32 v68, v68, v215
	v_sub_f32_e32 v69, v69, v215
	v_sub_f32_e32 v74, v74, v215
	v_sub_f32_e32 v75, v75, v215
	v_sub_f32_e32 v76, v76, v215
	v_sub_f32_e32 v77, v77, v215
	v_sub_f32_e32 v82, v82, v215
	v_sub_f32_e32 v83, v83, v215
	v_sub_f32_e32 v84, v84, v215
	v_sub_f32_e32 v85, v85, v215
	v_sub_f32_e32 v90, v90, v215
	v_sub_f32_e32 v91, v91, v215
	v_sub_f32_e32 v92, v92, v215
	v_sub_f32_e32 v93, v93, v215
	v_exp_f32_e32 v66, v66
	v_exp_f32_e32 v67, v67
	v_exp_f32_e32 v68, v68
	v_exp_f32_e32 v69, v69
	v_exp_f32_e32 v74, v74
	v_exp_f32_e32 v75, v75
	v_exp_f32_e32 v76, v76
	v_exp_f32_e32 v77, v77
	v_exp_f32_e32 v82, v82
	v_exp_f32_e32 v83, v83
	v_exp_f32_e32 v84, v84
	v_exp_f32_e32 v85, v85
	v_exp_f32_e32 v90, v90
	v_exp_f32_e32 v91, v91
	v_exp_f32_e32 v92, v92
	v_exp_f32_e32 v93, v93
	v_add_f32_e32 v217, v217, v66
	v_add_f32_e32 v217, v217, v67
	v_add_f32_e32 v217, v217, v68
	v_add_f32_e32 v217, v217, v69
	v_add_f32_e32 v217, v217, v74
	v_add_f32_e32 v217, v217, v75
	v_add_f32_e32 v217, v217, v76
	v_add_f32_e32 v217, v217, v77
	v_add_f32_e32 v217, v217, v82
	v_add_f32_e32 v217, v217, v83
	v_add_f32_e32 v217, v217, v84
	v_add_f32_e32 v217, v217, v85
	v_add_f32_e32 v217, v217, v90
	v_add_f32_e32 v217, v217, v91
	v_add_f32_e32 v217, v217, v92
	v_add_f32_e32 v217, v217, v93
	v_sub_f32_e32 v70, v70, v216
	v_sub_f32_e32 v71, v71, v216
	v_sub_f32_e32 v72, v72, v216
	v_sub_f32_e32 v73, v73, v216
	v_sub_f32_e32 v78, v78, v216
	v_sub_f32_e32 v79, v79, v216
	v_sub_f32_e32 v80, v80, v216
	v_sub_f32_e32 v81, v81, v216
	v_sub_f32_e32 v86, v86, v216
	v_sub_f32_e32 v87, v87, v216
	v_sub_f32_e32 v88, v88, v216
	v_sub_f32_e32 v89, v89, v216
	v_sub_f32_e32 v94, v94, v216
	v_sub_f32_e32 v95, v95, v216
	v_sub_f32_e32 v96, v96, v216
	v_sub_f32_e32 v97, v97, v216
	v_exp_f32_e32 v70, v70
	v_exp_f32_e32 v71, v71
	v_exp_f32_e32 v72, v72
	v_exp_f32_e32 v73, v73
	v_exp_f32_e32 v78, v78
	v_exp_f32_e32 v79, v79
	v_exp_f32_e32 v80, v80
	v_exp_f32_e32 v81, v81
	v_exp_f32_e32 v86, v86
	v_exp_f32_e32 v87, v87
	v_exp_f32_e32 v88, v88
	v_exp_f32_e32 v89, v89
	v_exp_f32_e32 v94, v94
	v_exp_f32_e32 v95, v95
	v_exp_f32_e32 v96, v96
	v_exp_f32_e32 v97, v97
	v_add_f32_e32 v218, v218, v70
	v_add_f32_e32 v218, v218, v71
	v_add_f32_e32 v218, v218, v72
	v_add_f32_e32 v218, v218, v73
	v_add_f32_e32 v218, v218, v78
	v_add_f32_e32 v218, v218, v79
	v_add_f32_e32 v218, v218, v80
	v_add_f32_e32 v218, v218, v81
	v_add_f32_e32 v218, v218, v86
	v_add_f32_e32 v218, v218, v87
	v_add_f32_e32 v218, v218, v88
	v_add_f32_e32 v218, v218, v89
	v_add_f32_e32 v218, v218, v94
	v_add_f32_e32 v218, v218, v95
	v_add_f32_e32 v218, v218, v96
	v_add_f32_e32 v218, v218, v97
.La3_e1x:
	ds_swizzle_b32 v188, v217 offset:0x401f
	s_waitcnt lgkmcnt(0)
	v_add_f32_e32 v217, v217, v188
	s_nop 0
	ds_bpermute_b32 v188, v214, v217
	s_waitcnt lgkmcnt(0)
	v_add_f32_e32 v217, v217, v188
	v_max_f32_e32 v217, 0xda24260, v217
	v_mov_b32_e32 v210, 1.0
	v_div_scale_f32 v206, s[44:45], v217, v217, v210
	v_rcp_f32_e32 v207, v206
	s_nop 0
	v_fma_f32 v208, -v206, v207, 1.0
	v_fmac_f32_e32 v207, v208, v207
	v_div_scale_f32 v208, vcc, v210, v217, v210
	v_mul_f32_e32 v209, v208, v207
	v_fma_f32 v211, -v206, v209, v208
	v_fmac_f32_e32 v209, v211, v207
	v_fma_f32 v206, -v206, v209, v208
	v_div_fmas_f32 v206, v206, v207, v209
	v_div_fixup_f32 v217, v206, v217, v210
	ds_swizzle_b32 v188, v218 offset:0x401f
	s_waitcnt lgkmcnt(0)
	v_add_f32_e32 v218, v218, v188
	s_nop 0
	ds_bpermute_b32 v188, v214, v218
	s_waitcnt lgkmcnt(0)
	v_add_f32_e32 v218, v218, v188
	v_max_f32_e32 v218, 0xda24260, v218
	v_mov_b32_e32 v210, 1.0
	v_div_scale_f32 v206, s[44:45], v218, v218, v210
	v_rcp_f32_e32 v207, v206
	s_nop 0
	v_fma_f32 v208, -v206, v207, 1.0
	v_fmac_f32_e32 v207, v208, v207
	v_div_scale_f32 v208, vcc, v210, v218, v210
	v_mul_f32_e32 v209, v208, v207
	v_fma_f32 v211, -v206, v209, v208
	v_fmac_f32_e32 v209, v211, v207
	v_fma_f32 v206, -v206, v209, v208
	v_div_fmas_f32 v206, v206, v207, v209
	v_div_fixup_f32 v218, v206, v218, v210
	v_mul_f32_e32 v34, v34, v217
	v_mul_f32_e32 v35, v35, v217
	v_mul_f32_e32 v36, v36, v217
	v_mul_f32_e32 v37, v37, v217
	v_mul_f32_e32 v42, v42, v217
	v_mul_f32_e32 v43, v43, v217
	v_mul_f32_e32 v44, v44, v217
	v_mul_f32_e32 v45, v45, v217
	v_mul_f32_e32 v50, v50, v217
	v_mul_f32_e32 v51, v51, v217
	v_mul_f32_e32 v52, v52, v217
	v_mul_f32_e32 v53, v53, v217
	v_mul_f32_e32 v58, v58, v217
	v_mul_f32_e32 v59, v59, v217
	v_mul_f32_e32 v60, v60, v217
	v_mul_f32_e32 v61, v61, v217
	v_mul_f32_e32 v38, v38, v218
	v_mul_f32_e32 v39, v39, v218
	v_mul_f32_e32 v40, v40, v218
	v_mul_f32_e32 v41, v41, v218
	v_mul_f32_e32 v46, v46, v218
	v_mul_f32_e32 v47, v47, v218
	v_mul_f32_e32 v48, v48, v218
	v_mul_f32_e32 v49, v49, v218
	v_mul_f32_e32 v54, v54, v218
	v_mul_f32_e32 v55, v55, v218
	v_mul_f32_e32 v56, v56, v218
	v_mul_f32_e32 v57, v57, v218
	v_mul_f32_e32 v62, v62, v218
	v_mul_f32_e32 v63, v63, v218
	v_mul_f32_e32 v64, v64, v218
	v_mul_f32_e32 v65, v65, v218
	v_add_f32_e32 v188, v34, v35
	v_add_f32_e32 v189, v36, v37
	ds_write_b32 v232, v188 offset:0
	ds_write_b32 v232, v189 offset:128
	v_add_f32_e32 v188, v42, v43
	v_add_f32_e32 v189, v44, v45
	ds_write_b32 v232, v188 offset:1024
	ds_write_b32 v232, v189 offset:1152
	v_add_f32_e32 v188, v50, v51
	v_add_f32_e32 v189, v52, v53
	ds_write_b32 v232, v188 offset:2048
	ds_write_b32 v232, v189 offset:2176
	v_add_f32_e32 v188, v58, v59
	v_add_f32_e32 v189, v60, v61
	ds_write_b32 v232, v188 offset:3072
	ds_write_b32 v232, v189 offset:3200
	v_add_f32_e32 v188, v38, v39
	v_add_f32_e32 v189, v40, v41
	ds_write_b32 v232, v188 offset:64
	ds_write_b32 v232, v189 offset:192
	v_add_f32_e32 v188, v46, v47
	v_add_f32_e32 v189, v48, v49
	ds_write_b32 v232, v188 offset:1088
	ds_write_b32 v232, v189 offset:1216
	v_add_f32_e32 v188, v54, v55
	v_add_f32_e32 v189, v56, v57
	ds_write_b32 v232, v188 offset:2112
	ds_write_b32 v232, v189 offset:2240
	v_add_f32_e32 v188, v62, v63
	v_add_f32_e32 v189, v64, v65
	ds_write_b32 v232, v188 offset:3136
	ds_write_b32 v232, v189 offset:3264
	v_cvt_pk_bf16_f32 v34, v34, v35
	v_cvt_pk_bf16_f32 v35, v36, v37
	v_cvt_pk_bf16_f32 v36, v42, v43
	v_cvt_pk_bf16_f32 v37, v44, v45
	v_cvt_pk_bf16_f32 v50, v50, v51
	v_cvt_pk_bf16_f32 v51, v52, v53
	v_cvt_pk_bf16_f32 v52, v58, v59
	v_cvt_pk_bf16_f32 v53, v60, v61
	v_cvt_pk_bf16_f32 v38, v38, v39
	v_cvt_pk_bf16_f32 v39, v40, v41
	v_cvt_pk_bf16_f32 v40, v46, v47
	v_cvt_pk_bf16_f32 v41, v48, v49
	v_cvt_pk_bf16_f32 v54, v54, v55
	v_cvt_pk_bf16_f32 v55, v56, v57
	v_cvt_pk_bf16_f32 v56, v62, v63
	v_cvt_pk_bf16_f32 v57, v64, v65
	ds_read_b64 v[148:149], v224 offset:0
	ds_read_b64 v[150:151], v225 offset:0
	ds_read_b64 v[152:153], v224 offset:2048
	ds_read_b64 v[154:155], v225 offset:2048
	ds_read_b64 v[156:157], v224 offset:4096
	ds_read_b64 v[158:159], v225 offset:4096
	ds_read_b64 v[184:185], v224 offset:6144
	ds_read_b64 v[186:187], v225 offset:6144
	s_waitcnt lgkmcnt(6)
	v_mfma_f32_16x16x32_bf16 v[2:5], v[148:151], v[34:37], v[2:5]
	v_mfma_f32_16x16x32_bf16 v[6:9], v[148:151], v[38:41], v[6:9]
	s_waitcnt lgkmcnt(4)
	v_mfma_f32_16x16x32_bf16 v[10:13], v[152:155], v[34:37], v[10:13]
	v_mfma_f32_16x16x32_bf16 v[14:17], v[152:155], v[38:41], v[14:17]
	s_waitcnt lgkmcnt(2)
	v_mfma_f32_16x16x32_bf16 v[18:21], v[156:159], v[34:37], v[18:21]
	v_mfma_f32_16x16x32_bf16 v[22:25], v[156:159], v[38:41], v[22:25]
	s_waitcnt lgkmcnt(0)
	v_mfma_f32_16x16x32_bf16 v[26:29], v[184:187], v[34:37], v[26:29]
	v_mfma_f32_16x16x32_bf16 v[30:33], v[184:187], v[38:41], v[30:33]
	ds_read_b64 v[148:149], v226 offset:0
	ds_read_b64 v[150:151], v227 offset:0
	ds_read_b64 v[152:153], v226 offset:2048
	ds_read_b64 v[154:155], v227 offset:2048
	ds_read_b64 v[156:157], v226 offset:4096
	ds_read_b64 v[158:159], v227 offset:4096
	ds_read_b64 v[184:185], v226 offset:6144
	ds_read_b64 v[186:187], v227 offset:6144
	s_waitcnt lgkmcnt(6)
	v_mfma_f32_16x16x32_bf16 v[2:5], v[148:151], v[50:53], v[2:5]
	v_mfma_f32_16x16x32_bf16 v[6:9], v[148:151], v[54:57], v[6:9]
	s_waitcnt lgkmcnt(4)
	v_mfma_f32_16x16x32_bf16 v[10:13], v[152:155], v[50:53], v[10:13]
	v_mfma_f32_16x16x32_bf16 v[14:17], v[152:155], v[54:57], v[14:17]
	s_waitcnt lgkmcnt(2)
	v_mfma_f32_16x16x32_bf16 v[18:21], v[156:159], v[50:53], v[18:21]
	v_mfma_f32_16x16x32_bf16 v[22:25], v[156:159], v[54:57], v[22:25]
	s_waitcnt lgkmcnt(0)
	v_mfma_f32_16x16x32_bf16 v[26:29], v[184:187], v[50:53], v[26:29]
	v_mfma_f32_16x16x32_bf16 v[30:33], v[184:187], v[54:57], v[30:33]
	s_cmp_eq_u32 s19, 2
	s_cbranch_scc0 .La3_p1x
	v_mul_f32_e32 v66, v66, v217
	v_mul_f32_e32 v67, v67, v217
	v_mul_f32_e32 v68, v68, v217
	v_mul_f32_e32 v69, v69, v217
	v_mul_f32_e32 v74, v74, v217
	v_mul_f32_e32 v75, v75, v217
	v_mul_f32_e32 v76, v76, v217
	v_mul_f32_e32 v77, v77, v217
	v_mul_f32_e32 v82, v82, v217
	v_mul_f32_e32 v83, v83, v217
	v_mul_f32_e32 v84, v84, v217
	v_mul_f32_e32 v85, v85, v217
	v_mul_f32_e32 v90, v90, v217
	v_mul_f32_e32 v91, v91, v217
	v_mul_f32_e32 v92, v92, v217
	v_mul_f32_e32 v93, v93, v217
	v_mul_f32_e32 v70, v70, v218
	v_mul_f32_e32 v71, v71, v218
	v_mul_f32_e32 v72, v72, v218
	v_mul_f32_e32 v73, v73, v218
	v_mul_f32_e32 v78, v78, v218
	v_mul_f32_e32 v79, v79, v218
	v_mul_f32_e32 v80, v80, v218
	v_mul_f32_e32 v81, v81, v218
	v_mul_f32_e32 v86, v86, v218
	v_mul_f32_e32 v87, v87, v218
	v_mul_f32_e32 v88, v88, v218
	v_mul_f32_e32 v89, v89, v218
	v_mul_f32_e32 v94, v94, v218
	v_mul_f32_e32 v95, v95, v218
	v_mul_f32_e32 v96, v96, v218
	v_mul_f32_e32 v97, v97, v218
	v_add_f32_e32 v188, v66, v67
	v_add_f32_e32 v189, v68, v69
	ds_write_b32 v232, v188 offset:4096
	ds_write_b32 v232, v189 offset:4224
	v_add_f32_e32 v188, v74, v75
	v_add_f32_e32 v189, v76, v77
	ds_write_b32 v232, v188 offset:5120
	ds_write_b32 v232, v189 offset:5248
	v_add_f32_e32 v188, v82, v83
	v_add_f32_e32 v189, v84, v85
	ds_write_b32 v232, v188 offset:6144
	ds_write_b32 v232, v189 offset:6272
	v_add_f32_e32 v188, v90, v91
	v_add_f32_e32 v189, v92, v93
	ds_write_b32 v232, v188 offset:7168
	ds_write_b32 v232, v189 offset:7296
	v_add_f32_e32 v188, v70, v71
	v_add_f32_e32 v189, v72, v73
	ds_write_b32 v232, v188 offset:4160
	ds_write_b32 v232, v189 offset:4288
	v_add_f32_e32 v188, v78, v79
	v_add_f32_e32 v189, v80, v81
	ds_write_b32 v232, v188 offset:5184
	ds_write_b32 v232, v189 offset:5312
	v_add_f32_e32 v188, v86, v87
	v_add_f32_e32 v189, v88, v89
	ds_write_b32 v232, v188 offset:6208
	ds_write_b32 v232, v189 offset:6336
	v_add_f32_e32 v188, v94, v95
	v_add_f32_e32 v189, v96, v97
	ds_write_b32 v232, v188 offset:7232
	ds_write_b32 v232, v189 offset:7360
	v_cvt_pk_bf16_f32 v66, v66, v67
	v_cvt_pk_bf16_f32 v67, v68, v69
	v_cvt_pk_bf16_f32 v68, v74, v75
	v_cvt_pk_bf16_f32 v69, v76, v77
	v_cvt_pk_bf16_f32 v82, v82, v83
	v_cvt_pk_bf16_f32 v83, v84, v85
	v_cvt_pk_bf16_f32 v84, v90, v91
	v_cvt_pk_bf16_f32 v85, v92, v93
	v_cvt_pk_bf16_f32 v70, v70, v71
	v_cvt_pk_bf16_f32 v71, v72, v73
	v_cvt_pk_bf16_f32 v72, v78, v79
	v_cvt_pk_bf16_f32 v73, v80, v81
	v_cvt_pk_bf16_f32 v86, v86, v87
	v_cvt_pk_bf16_f32 v87, v88, v89
	v_cvt_pk_bf16_f32 v88, v94, v95
	v_cvt_pk_bf16_f32 v89, v96, v97
	ds_read_b64 v[148:149], v224 offset:32768
	ds_read_b64 v[150:151], v225 offset:32768
	ds_read_b64 v[152:153], v224 offset:34816
	ds_read_b64 v[154:155], v225 offset:34816
	ds_read_b64 v[156:157], v224 offset:36864
	ds_read_b64 v[158:159], v225 offset:36864
	ds_read_b64 v[184:185], v224 offset:38912
	ds_read_b64 v[186:187], v225 offset:38912
	s_waitcnt lgkmcnt(6)
	v_mfma_f32_16x16x32_bf16 v[2:5], v[148:151], v[66:69], v[2:5]
	v_mfma_f32_16x16x32_bf16 v[6:9], v[148:151], v[70:73], v[6:9]
	s_waitcnt lgkmcnt(4)
	v_mfma_f32_16x16x32_bf16 v[10:13], v[152:155], v[66:69], v[10:13]
	v_mfma_f32_16x16x32_bf16 v[14:17], v[152:155], v[70:73], v[14:17]
	s_waitcnt lgkmcnt(2)
	v_mfma_f32_16x16x32_bf16 v[18:21], v[156:159], v[66:69], v[18:21]
	v_mfma_f32_16x16x32_bf16 v[22:25], v[156:159], v[70:73], v[22:25]
	s_waitcnt lgkmcnt(0)
	v_mfma_f32_16x16x32_bf16 v[26:29], v[184:187], v[66:69], v[26:29]
	v_mfma_f32_16x16x32_bf16 v[30:33], v[184:187], v[70:73], v[30:33]
	ds_read_b64 v[148:149], v226 offset:32768
	ds_read_b64 v[150:151], v227 offset:32768
	ds_read_b64 v[152:153], v226 offset:34816
	ds_read_b64 v[154:155], v227 offset:34816
	ds_read_b64 v[156:157], v226 offset:36864
	ds_read_b64 v[158:159], v227 offset:36864
	ds_read_b64 v[184:185], v226 offset:38912
	ds_read_b64 v[186:187], v227 offset:38912
	s_waitcnt lgkmcnt(6)
	v_mfma_f32_16x16x32_bf16 v[2:5], v[148:151], v[82:85], v[2:5]
	v_mfma_f32_16x16x32_bf16 v[6:9], v[148:151], v[86:89], v[6:9]
	s_waitcnt lgkmcnt(4)
	v_mfma_f32_16x16x32_bf16 v[10:13], v[152:155], v[82:85], v[10:13]
	v_mfma_f32_16x16x32_bf16 v[14:17], v[152:155], v[86:89], v[14:17]
	s_waitcnt lgkmcnt(2)
	v_mfma_f32_16x16x32_bf16 v[18:21], v[156:159], v[82:85], v[18:21]
	v_mfma_f32_16x16x32_bf16 v[22:25], v[156:159], v[86:89], v[22:25]
	s_waitcnt lgkmcnt(0)
	v_mfma_f32_16x16x32_bf16 v[26:29], v[184:187], v[82:85], v[26:29]
	v_mfma_f32_16x16x32_bf16 v[30:33], v[184:187], v[86:89], v[30:33]
.La3_p1x:
	s_waitcnt lgkmcnt(0)
	s_barrier
	s_nop 7
	v_lshlrev_b32_e32 v190, 16, v220
	v_mul_f32_e32 v190, 0xbfb8aa3b, v190
	v_exp_f32_e32 v190, v190
	s_nop 0
	v_add_f32_e32 v190, 1.0, v190
	v_rcp_f32_e32 v190, v190
	v_lshlrev_b32_e32 v191, 16, v221
	v_mul_f32_e32 v191, 0xbfb8aa3b, v191
	v_exp_f32_e32 v191, v191
	s_nop 0
	v_add_f32_e32 v191, 1.0, v191
	v_rcp_f32_e32 v191, v191
	s_nop 0
	v_mul_f32_e32 v206, v2, v190
	v_mul_f32_e32 v207, v3, v190
	v_mul_f32_e32 v208, v4, v190
	v_mul_f32_e32 v209, v5, v190
	v_cvt_pk_bf16_f32 v147, v206, v207
	v_cvt_pk_bf16_f32 v146, v208, v209
	v_mul_f32_e32 v206, v10, v190
	v_mul_f32_e32 v207, v11, v190
	v_mul_f32_e32 v208, v12, v190
	v_mul_f32_e32 v209, v13, v190
	v_cvt_pk_bf16_f32 v145, v206, v207
	v_cvt_pk_bf16_f32 v144, v208, v209
	v_mul_f32_e32 v206, v18, v190
	v_mul_f32_e32 v207, v19, v190
	v_mul_f32_e32 v208, v20, v190
	v_mul_f32_e32 v209, v21, v190
	v_cvt_pk_bf16_f32 v143, v206, v207
	v_cvt_pk_bf16_f32 v142, v208, v209
	v_mul_f32_e32 v206, v26, v190
	v_mul_f32_e32 v207, v27, v190
	v_mul_f32_e32 v208, v28, v190
	v_mul_f32_e32 v209, v29, v190
	v_cvt_pk_bf16_f32 v141, v206, v207
	v_cvt_pk_bf16_f32 v140, v208, v209
	v_mul_f32_e32 v206, v6, v191
	v_mul_f32_e32 v207, v7, v191
	v_mul_f32_e32 v208, v8, v191
	v_mul_f32_e32 v209, v9, v191
	v_cvt_pk_bf16_f32 v139, v206, v207
	v_cvt_pk_bf16_f32 v138, v208, v209
	v_mul_f32_e32 v206, v14, v191
	v_mul_f32_e32 v207, v15, v191
	v_mul_f32_e32 v208, v16, v191
	v_mul_f32_e32 v209, v17, v191
	v_cvt_pk_bf16_f32 v137, v206, v207
	v_cvt_pk_bf16_f32 v136, v208, v209
	v_mul_f32_e32 v206, v22, v191
	v_mul_f32_e32 v207, v23, v191
	v_mul_f32_e32 v208, v24, v191
	v_mul_f32_e32 v209, v25, v191
	v_cvt_pk_bf16_f32 v123, v206, v207
	v_cvt_pk_bf16_f32 v122, v208, v209
	v_mul_f32_e32 v206, v30, v191
	v_mul_f32_e32 v207, v31, v191
	v_mul_f32_e32 v208, v32, v191
	v_mul_f32_e32 v209, v33, v191
	v_cvt_pk_bf16_f32 v121, v206, v207
	v_cvt_pk_bf16_f32 v120, v208, v209
	v_and_b32_e32 v188, 63, v163
	s_cmp_lt_u32 s4, 16
	s_cbranch_scc0 .La3_tk_rank
	s_add_i32 s28, s4, 1
	s_bfm_b64 s[44:45], s28, 0
	v_mov_b32_e32 v190, s44
	v_mov_b32_e32 v191, s45
	s_lshl_b32 s29, s7, 6
	v_mov_b32_e32 v189, s29
	s_mov_b64 exec, 1
	ds_write_b64 v189, v[190:191] offset:32768
	ds_write_b64 v189, v[190:191] offset:32776
	ds_write_b64 v189, v[190:191] offset:32784
	ds_write_b64 v189, v[190:191] offset:32792
	ds_write_b64 v189, v[190:191] offset:32800
	ds_write_b64 v189, v[190:191] offset:32808
	ds_write_b64 v189, v[190:191] offset:32816
	ds_write_b64 v189, v[190:191] offset:32824
	s_mov_b64 exec, -1
	s_branch .La3_tk_done
.La3_tk_rank:
	s_lshl_b32 s28, s7, 5
	v_lshl_add_u32 v189, v188, 7, s28
	ds_read_b128 v[66:69], v189 offset:16384
	ds_read_b128 v[70:73], v189 offset:16400
	s_waitcnt lgkmcnt(0)
	v_mov_b32_e32 v34, v66
	v_mov_b32_e32 v35, v67
	v_mov_b32_e32 v36, v68
	v_mov_b32_e32 v37, v69
	v_mov_b32_e32 v38, v70
	v_mov_b32_e32 v39, v71
	v_mov_b32_e32 v40, v72
	v_mov_b32_e32 v41, v73
	ds_read_b128 v[66:69], v189 offset:24576
	ds_read_b128 v[70:73], v189 offset:24592
	s_waitcnt lgkmcnt(0)
	v_add_f32_e32 v34, v34, v66
	v_add_f32_e32 v35, v35, v67
	v_add_f32_e32 v36, v36, v68
	v_add_f32_e32 v37, v37, v69
	v_add_f32_e32 v38, v38, v70
	v_add_f32_e32 v39, v39, v71
	v_add_f32_e32 v40, v40, v72
	v_add_f32_e32 v41, v41, v73
	ds_read_b128 v[66:69], v189 offset:49152
	ds_read_b128 v[70:73], v189 offset:49168
	s_waitcnt lgkmcnt(0)
	v_add_f32_e32 v34, v34, v66
	v_add_f32_e32 v35, v35, v67
	v_add_f32_e32 v36, v36, v68
	v_add_f32_e32 v37, v37, v69
	v_add_f32_e32 v38, v38, v70
	v_add_f32_e32 v39, v39, v71
	v_add_f32_e32 v40, v40, v72
	v_add_f32_e32 v41, v41, v73
	ds_read_b128 v[66:69], v189 offset:57344
	ds_read_b128 v[70:73], v189 offset:57360
	s_waitcnt lgkmcnt(0)
	v_add_f32_e32 v34, v34, v66
	v_add_f32_e32 v35, v35, v67
	v_add_f32_e32 v36, v36, v68
	v_add_f32_e32 v37, v37, v69
	v_add_f32_e32 v38, v38, v70
	v_add_f32_e32 v39, v39, v71
	v_add_f32_e32 v40, v40, v72
	v_add_f32_e32 v41, v41, v73
	v_cmp_ge_u32_e64 s[54:55], s4, v188
	v_cmp_eq_u32_e64 s[56:57], 0, v188
	v_cmp_eq_u32_e64 s[58:59], s4, v188
	s_or_b64 s[56:57], s[56:57], s[58:59]
	s_add_i32 s28, s4, -1
	v_cmp_eq_u32_e64 s[58:59], s28, v188
	s_or_b64 s[56:57], s[56:57], s[58:59]
	s_lshl_b32 s29, s7, 6
	v_mov_b32_e32 v189, s29
	v_mov_b32_e32 v206, 0x461c4000
	v_cndmask_b32_e64 v50, v34, v206, s[56:57]
	v_add_u32_e32 v50, 1, v50
	v_cndmask_b32_e64 v50, 0, v50, s[54:55]
	s_mov_b32 s48, 0
	s_or_b32 s49, s48, 0x40000000
	v_cmp_le_u32_e32 vcc, s49, v50
	s_bcnt1_i32_b64 s50, vcc
	s_cmp_ge_u32 s50, 16
	s_cselect_b32 s48, s49, s48
	s_or_b32 s49, s48, 0x20000000
	v_cmp_le_u32_e32 vcc, s49, v50
	s_bcnt1_i32_b64 s50, vcc
	s_cmp_ge_u32 s50, 16
	s_cselect_b32 s48, s49, s48
	s_or_b32 s49, s48, 0x10000000
	v_cmp_le_u32_e32 vcc, s49, v50
	s_bcnt1_i32_b64 s50, vcc
	s_cmp_ge_u32 s50, 16
	s_cselect_b32 s48, s49, s48
	s_or_b32 s49, s48, 0x8000000
	v_cmp_le_u32_e32 vcc, s49, v50
	s_bcnt1_i32_b64 s50, vcc
	s_cmp_ge_u32 s50, 16
	s_cselect_b32 s48, s49, s48
	s_or_b32 s49, s48, 0x4000000
	v_cmp_le_u32_e32 vcc, s49, v50
	s_bcnt1_i32_b64 s50, vcc
	s_cmp_ge_u32 s50, 16
	s_cselect_b32 s48, s49, s48
	s_or_b32 s49, s48, 0x2000000
	v_cmp_le_u32_e32 vcc, s49, v50
	s_bcnt1_i32_b64 s50, vcc
	s_cmp_ge_u32 s50, 16
	s_cselect_b32 s48, s49, s48
	s_or_b32 s49, s48, 0x1000000
	v_cmp_le_u32_e32 vcc, s49, v50
	s_bcnt1_i32_b64 s50, vcc
	s_cmp_ge_u32 s50, 16
	s_cselect_b32 s48, s49, s48
	s_or_b32 s49, s48, 0x800000
	v_cmp_le_u32_e32 vcc, s49, v50
	s_bcnt1_i32_b64 s50, vcc
	s_cmp_ge_u32 s50, 16
	s_cselect_b32 s48, s49, s48
	s_or_b32 s49, s48, 0x400000
	v_cmp_le_u32_e32 vcc, s49, v50
	s_bcnt1_i32_b64 s50, vcc
	s_cmp_ge_u32 s50, 16
	s_cselect_b32 s48, s49, s48
	s_or_b32 s49, s48, 0x200000
	v_cmp_le_u32_e32 vcc, s49, v50
	s_bcnt1_i32_b64 s50, vcc
	s_cmp_ge_u32 s50, 16
	s_cselect_b32 s48, s49, s48
	s_or_b32 s49, s48, 0x100000
	v_cmp_le_u32_e32 vcc, s49, v50
	s_bcnt1_i32_b64 s50, vcc
	s_cmp_ge_u32 s50, 16
	s_cselect_b32 s48, s49, s48
	s_or_b32 s49, s48, 0x80000
	v_cmp_le_u32_e32 vcc, s49, v50
	s_bcnt1_i32_b64 s50, vcc
	s_cmp_ge_u32 s50, 16
	s_cselect_b32 s48, s49, s48
	s_or_b32 s49, s48, 0x40000
	v_cmp_le_u32_e32 vcc, s49, v50
	s_bcnt1_i32_b64 s50, vcc
	s_cmp_ge_u32 s50, 16
	s_cselect_b32 s48, s49, s48
	s_or_b32 s49, s48, 0x20000
	v_cmp_le_u32_e32 vcc, s49, v50
	s_bcnt1_i32_b64 s50, vcc
	s_cmp_ge_u32 s50, 16
	s_cselect_b32 s48, s49, s48
	s_or_b32 s49, s48, 0x10000
	v_cmp_le_u32_e32 vcc, s49, v50
	s_bcnt1_i32_b64 s50, vcc
	s_cmp_ge_u32 s50, 16
	s_cselect_b32 s48, s49, s48
	s_or_b32 s49, s48, 0x8000
	v_cmp_le_u32_e32 vcc, s49, v50
	s_bcnt1_i32_b64 s50, vcc
	s_cmp_ge_u32 s50, 16
	s_cselect_b32 s48, s49, s48
	s_or_b32 s49, s48, 0x4000
	v_cmp_le_u32_e32 vcc, s49, v50
	s_bcnt1_i32_b64 s50, vcc
	s_cmp_ge_u32 s50, 16
	s_cselect_b32 s48, s49, s48
	s_or_b32 s49, s48, 0x2000
	v_cmp_le_u32_e32 vcc, s49, v50
	s_bcnt1_i32_b64 s50, vcc
	s_cmp_ge_u32 s50, 16
	s_cselect_b32 s48, s49, s48
	s_or_b32 s49, s48, 0x1000
	v_cmp_le_u32_e32 vcc, s49, v50
	s_bcnt1_i32_b64 s50, vcc
	s_cmp_ge_u32 s50, 16
	s_cselect_b32 s48, s49, s48
	s_or_b32 s49, s48, 0x800
	v_cmp_le_u32_e32 vcc, s49, v50
	s_bcnt1_i32_b64 s50, vcc
	s_cmp_ge_u32 s50, 16
	s_cselect_b32 s48, s49, s48
	s_or_b32 s49, s48, 0x400
	v_cmp_le_u32_e32 vcc, s49, v50
	s_bcnt1_i32_b64 s50, vcc
	s_cmp_ge_u32 s50, 16
	s_cselect_b32 s48, s49, s48
	s_or_b32 s49, s48, 0x200
	v_cmp_le_u32_e32 vcc, s49, v50
	s_bcnt1_i32_b64 s50, vcc
	s_cmp_ge_u32 s50, 16
	s_cselect_b32 s48, s49, s48
	s_or_b32 s49, s48, 0x100
	v_cmp_le_u32_e32 vcc, s49, v50
	s_bcnt1_i32_b64 s50, vcc
	s_cmp_ge_u32 s50, 16
	s_cselect_b32 s48, s49, s48
	s_or_b32 s49, s48, 0x80
	v_cmp_le_u32_e32 vcc, s49, v50
	s_bcnt1_i32_b64 s50, vcc
	s_cmp_ge_u32 s50, 16
	s_cselect_b32 s48, s49, s48
	s_or_b32 s49, s48, 0x40
	v_cmp_le_u32_e32 vcc, s49, v50
	s_bcnt1_i32_b64 s50, vcc
	s_cmp_ge_u32 s50, 16
	s_cselect_b32 s48, s49, s48
	s_or_b32 s49, s48, 0x20
	v_cmp_le_u32_e32 vcc, s49, v50
	s_bcnt1_i32_b64 s50, vcc
	s_cmp_ge_u32 s50, 16
	s_cselect_b32 s48, s49, s48
	s_or_b32 s49, s48, 0x10
	v_cmp_le_u32_e32 vcc, s49, v50
	s_bcnt1_i32_b64 s50, vcc
	s_cmp_ge_u32 s50, 16
	s_cselect_b32 s48, s49, s48
	s_or_b32 s49, s48, 0x8
	v_cmp_le_u32_e32 vcc, s49, v50
	s_bcnt1_i32_b64 s50, vcc
	s_cmp_ge_u32 s50, 16
	s_cselect_b32 s48, s49, s48
	s_or_b32 s49, s48, 0x4
	v_cmp_le_u32_e32 vcc, s49, v50
	s_bcnt1_i32_b64 s50, vcc
	s_cmp_ge_u32 s50, 16
	s_cselect_b32 s48, s49, s48
	s_or_b32 s49, s48, 0x2
	v_cmp_le_u32_e32 vcc, s49, v50
	s_bcnt1_i32_b64 s50, vcc
	s_cmp_ge_u32 s50, 16
	s_cselect_b32 s48, s49, s48
	s_or_b32 s49, s48, 0x1
	v_cmp_le_u32_e32 vcc, s49, v50
	s_bcnt1_i32_b64 s50, vcc
	s_cmp_ge_u32 s50, 16
	s_cselect_b32 s48, s49, s48
	v_cmp_lt_u32_e64 s[44:45], s48, v50
	v_cmp_eq_u32_e64 s[46:47], s48, v50
	s_bcnt1_i32_b64 s50, s[44:45]
	s_sub_i32 s51, 16, s50
.La3_tk_tie0:
	s_cmp_lt_i32 s51, 1
	s_cbranch_scc1 .La3_tk_w0
	s_ff1_i32_b64 s52, s[46:47]
	s_lshl_b64 s[30:31], 1, s52
	s_or_b64 s[44:45], s[44:45], s[30:31]
	s_andn2_b64 s[46:47], s[46:47], s[30:31]
	s_add_i32 s51, s51, -1
	s_branch .La3_tk_tie0
.La3_tk_w0:
	v_mov_b32_e32 v190, s44
	v_mov_b32_e32 v191, s45
	s_mov_b64 exec, 1
	ds_write_b64 v189, v[190:191] offset:32768
	s_mov_b64 exec, -1
	v_cndmask_b32_e64 v50, v35, v206, s[56:57]
	v_add_u32_e32 v50, 1, v50
	v_cndmask_b32_e64 v50, 0, v50, s[54:55]
	s_mov_b32 s48, 0
	s_or_b32 s49, s48, 0x40000000
	v_cmp_le_u32_e32 vcc, s49, v50
	s_bcnt1_i32_b64 s50, vcc
	s_cmp_ge_u32 s50, 16
	s_cselect_b32 s48, s49, s48
	s_or_b32 s49, s48, 0x20000000
	v_cmp_le_u32_e32 vcc, s49, v50
	s_bcnt1_i32_b64 s50, vcc
	s_cmp_ge_u32 s50, 16
	s_cselect_b32 s48, s49, s48
	s_or_b32 s49, s48, 0x10000000
	v_cmp_le_u32_e32 vcc, s49, v50
	s_bcnt1_i32_b64 s50, vcc
	s_cmp_ge_u32 s50, 16
	s_cselect_b32 s48, s49, s48
	s_or_b32 s49, s48, 0x8000000
	v_cmp_le_u32_e32 vcc, s49, v50
	s_bcnt1_i32_b64 s50, vcc
	s_cmp_ge_u32 s50, 16
	s_cselect_b32 s48, s49, s48
	s_or_b32 s49, s48, 0x4000000
	v_cmp_le_u32_e32 vcc, s49, v50
	s_bcnt1_i32_b64 s50, vcc
	s_cmp_ge_u32 s50, 16
	s_cselect_b32 s48, s49, s48
	s_or_b32 s49, s48, 0x2000000
	v_cmp_le_u32_e32 vcc, s49, v50
	s_bcnt1_i32_b64 s50, vcc
	s_cmp_ge_u32 s50, 16
	s_cselect_b32 s48, s49, s48
	s_or_b32 s49, s48, 0x1000000
	v_cmp_le_u32_e32 vcc, s49, v50
	s_bcnt1_i32_b64 s50, vcc
	s_cmp_ge_u32 s50, 16
	s_cselect_b32 s48, s49, s48
	s_or_b32 s49, s48, 0x800000
	v_cmp_le_u32_e32 vcc, s49, v50
	s_bcnt1_i32_b64 s50, vcc
	s_cmp_ge_u32 s50, 16
	s_cselect_b32 s48, s49, s48
	s_or_b32 s49, s48, 0x400000
	v_cmp_le_u32_e32 vcc, s49, v50
	s_bcnt1_i32_b64 s50, vcc
	s_cmp_ge_u32 s50, 16
	s_cselect_b32 s48, s49, s48
	s_or_b32 s49, s48, 0x200000
	v_cmp_le_u32_e32 vcc, s49, v50
	s_bcnt1_i32_b64 s50, vcc
	s_cmp_ge_u32 s50, 16
	s_cselect_b32 s48, s49, s48
	s_or_b32 s49, s48, 0x100000
	v_cmp_le_u32_e32 vcc, s49, v50
	s_bcnt1_i32_b64 s50, vcc
	s_cmp_ge_u32 s50, 16
	s_cselect_b32 s48, s49, s48
	s_or_b32 s49, s48, 0x80000
	v_cmp_le_u32_e32 vcc, s49, v50
	s_bcnt1_i32_b64 s50, vcc
	s_cmp_ge_u32 s50, 16
	s_cselect_b32 s48, s49, s48
	s_or_b32 s49, s48, 0x40000
	v_cmp_le_u32_e32 vcc, s49, v50
	s_bcnt1_i32_b64 s50, vcc
	s_cmp_ge_u32 s50, 16
	s_cselect_b32 s48, s49, s48
	s_or_b32 s49, s48, 0x20000
	v_cmp_le_u32_e32 vcc, s49, v50
	s_bcnt1_i32_b64 s50, vcc
	s_cmp_ge_u32 s50, 16
	s_cselect_b32 s48, s49, s48
	s_or_b32 s49, s48, 0x10000
	v_cmp_le_u32_e32 vcc, s49, v50
	s_bcnt1_i32_b64 s50, vcc
	s_cmp_ge_u32 s50, 16
	s_cselect_b32 s48, s49, s48
	s_or_b32 s49, s48, 0x8000
	v_cmp_le_u32_e32 vcc, s49, v50
	s_bcnt1_i32_b64 s50, vcc
	s_cmp_ge_u32 s50, 16
	s_cselect_b32 s48, s49, s48
	s_or_b32 s49, s48, 0x4000
	v_cmp_le_u32_e32 vcc, s49, v50
	s_bcnt1_i32_b64 s50, vcc
	s_cmp_ge_u32 s50, 16
	s_cselect_b32 s48, s49, s48
	s_or_b32 s49, s48, 0x2000
	v_cmp_le_u32_e32 vcc, s49, v50
	s_bcnt1_i32_b64 s50, vcc
	s_cmp_ge_u32 s50, 16
	s_cselect_b32 s48, s49, s48
	s_or_b32 s49, s48, 0x1000
	v_cmp_le_u32_e32 vcc, s49, v50
	s_bcnt1_i32_b64 s50, vcc
	s_cmp_ge_u32 s50, 16
	s_cselect_b32 s48, s49, s48
	s_or_b32 s49, s48, 0x800
	v_cmp_le_u32_e32 vcc, s49, v50
	s_bcnt1_i32_b64 s50, vcc
	s_cmp_ge_u32 s50, 16
	s_cselect_b32 s48, s49, s48
	s_or_b32 s49, s48, 0x400
	v_cmp_le_u32_e32 vcc, s49, v50
	s_bcnt1_i32_b64 s50, vcc
	s_cmp_ge_u32 s50, 16
	s_cselect_b32 s48, s49, s48
	s_or_b32 s49, s48, 0x200
	v_cmp_le_u32_e32 vcc, s49, v50
	s_bcnt1_i32_b64 s50, vcc
	s_cmp_ge_u32 s50, 16
	s_cselect_b32 s48, s49, s48
	s_or_b32 s49, s48, 0x100
	v_cmp_le_u32_e32 vcc, s49, v50
	s_bcnt1_i32_b64 s50, vcc
	s_cmp_ge_u32 s50, 16
	s_cselect_b32 s48, s49, s48
	s_or_b32 s49, s48, 0x80
	v_cmp_le_u32_e32 vcc, s49, v50
	s_bcnt1_i32_b64 s50, vcc
	s_cmp_ge_u32 s50, 16
	s_cselect_b32 s48, s49, s48
	s_or_b32 s49, s48, 0x40
	v_cmp_le_u32_e32 vcc, s49, v50
	s_bcnt1_i32_b64 s50, vcc
	s_cmp_ge_u32 s50, 16
	s_cselect_b32 s48, s49, s48
	s_or_b32 s49, s48, 0x20
	v_cmp_le_u32_e32 vcc, s49, v50
	s_bcnt1_i32_b64 s50, vcc
	s_cmp_ge_u32 s50, 16
	s_cselect_b32 s48, s49, s48
	s_or_b32 s49, s48, 0x10
	v_cmp_le_u32_e32 vcc, s49, v50
	s_bcnt1_i32_b64 s50, vcc
	s_cmp_ge_u32 s50, 16
	s_cselect_b32 s48, s49, s48
	s_or_b32 s49, s48, 0x8
	v_cmp_le_u32_e32 vcc, s49, v50
	s_bcnt1_i32_b64 s50, vcc
	s_cmp_ge_u32 s50, 16
	s_cselect_b32 s48, s49, s48
	s_or_b32 s49, s48, 0x4
	v_cmp_le_u32_e32 vcc, s49, v50
	s_bcnt1_i32_b64 s50, vcc
	s_cmp_ge_u32 s50, 16
	s_cselect_b32 s48, s49, s48
	s_or_b32 s49, s48, 0x2
	v_cmp_le_u32_e32 vcc, s49, v50
	s_bcnt1_i32_b64 s50, vcc
	s_cmp_ge_u32 s50, 16
	s_cselect_b32 s48, s49, s48
	s_or_b32 s49, s48, 0x1
	v_cmp_le_u32_e32 vcc, s49, v50
	s_bcnt1_i32_b64 s50, vcc
	s_cmp_ge_u32 s50, 16
	s_cselect_b32 s48, s49, s48
	v_cmp_lt_u32_e64 s[44:45], s48, v50
	v_cmp_eq_u32_e64 s[46:47], s48, v50
	s_bcnt1_i32_b64 s50, s[44:45]
	s_sub_i32 s51, 16, s50

.La3_tk_w1:
	v_mov_b32_e32 v190, s44
	v_mov_b32_e32 v191, s45
	s_mov_b64 exec, 1
	ds_write_b64 v189, v[190:191] offset:32776
	s_mov_b64 exec, -1
	v_cndmask_b32_e64 v50, v36, v206, s[56:57]
	v_add_u32_e32 v50, 1, v50
	v_cndmask_b32_e64 v50, 0, v50, s[54:55]
	s_mov_b32 s48, 0
	s_or_b32 s49, s48, 0x40000000
	v_cmp_le_u32_e32 vcc, s49, v50
	s_bcnt1_i32_b64 s50, vcc
	s_cmp_ge_u32 s50, 16
	s_cselect_b32 s48, s49, s48
	s_or_b32 s49, s48, 0x20000000
	v_cmp_le_u32_e32 vcc, s49, v50
	s_bcnt1_i32_b64 s50, vcc
	s_cmp_ge_u32 s50, 16
	s_cselect_b32 s48, s49, s48
	s_or_b32 s49, s48, 0x10000000
	v_cmp_le_u32_e32 vcc, s49, v50
	s_bcnt1_i32_b64 s50, vcc
	s_cmp_ge_u32 s50, 16
	s_cselect_b32 s48, s49, s48
	s_or_b32 s49, s48, 0x8000000
	v_cmp_le_u32_e32 vcc, s49, v50
	s_bcnt1_i32_b64 s50, vcc
	s_cmp_ge_u32 s50, 16
	s_cselect_b32 s48, s49, s48
	s_or_b32 s49, s48, 0x4000000
	v_cmp_le_u32_e32 vcc, s49, v50
	s_bcnt1_i32_b64 s50, vcc
	s_cmp_ge_u32 s50, 16
	s_cselect_b32 s48, s49, s48
	s_or_b32 s49, s48, 0x2000000
	v_cmp_le_u32_e32 vcc, s49, v50
	s_bcnt1_i32_b64 s50, vcc
	s_cmp_ge_u32 s50, 16
	s_cselect_b32 s48, s49, s48
	s_or_b32 s49, s48, 0x1000000
	v_cmp_le_u32_e32 vcc, s49, v50
	s_bcnt1_i32_b64 s50, vcc
	s_cmp_ge_u32 s50, 16
	s_cselect_b32 s48, s49, s48
	s_or_b32 s49, s48, 0x800000
	v_cmp_le_u32_e32 vcc, s49, v50
	s_bcnt1_i32_b64 s50, vcc
	s_cmp_ge_u32 s50, 16
	s_cselect_b32 s48, s49, s48
	s_or_b32 s49, s48, 0x400000
	v_cmp_le_u32_e32 vcc, s49, v50
	s_bcnt1_i32_b64 s50, vcc
	s_cmp_ge_u32 s50, 16
	s_cselect_b32 s48, s49, s48
	s_or_b32 s49, s48, 0x200000
	v_cmp_le_u32_e32 vcc, s49, v50
	s_bcnt1_i32_b64 s50, vcc
	s_cmp_ge_u32 s50, 16
	s_cselect_b32 s48, s49, s48
	s_or_b32 s49, s48, 0x100000
	v_cmp_le_u32_e32 vcc, s49, v50
	s_bcnt1_i32_b64 s50, vcc
	s_cmp_ge_u32 s50, 16
	s_cselect_b32 s48, s49, s48
	s_or_b32 s49, s48, 0x80000
	v_cmp_le_u32_e32 vcc, s49, v50
	s_bcnt1_i32_b64 s50, vcc
	s_cmp_ge_u32 s50, 16
	s_cselect_b32 s48, s49, s48
	s_or_b32 s49, s48, 0x40000
	v_cmp_le_u32_e32 vcc, s49, v50
	s_bcnt1_i32_b64 s50, vcc
	s_cmp_ge_u32 s50, 16
	s_cselect_b32 s48, s49, s48
	s_or_b32 s49, s48, 0x20000
	v_cmp_le_u32_e32 vcc, s49, v50
	s_bcnt1_i32_b64 s50, vcc
	s_cmp_ge_u32 s50, 16
	s_cselect_b32 s48, s49, s48
	s_or_b32 s49, s48, 0x10000
	v_cmp_le_u32_e32 vcc, s49, v50
	s_bcnt1_i32_b64 s50, vcc
	s_cmp_ge_u32 s50, 16
	s_cselect_b32 s48, s49, s48
	s_or_b32 s49, s48, 0x8000
	v_cmp_le_u32_e32 vcc, s49, v50
	s_bcnt1_i32_b64 s50, vcc
	s_cmp_ge_u32 s50, 16
	s_cselect_b32 s48, s49, s48
	s_or_b32 s49, s48, 0x4000
	v_cmp_le_u32_e32 vcc, s49, v50
	s_bcnt1_i32_b64 s50, vcc
	s_cmp_ge_u32 s50, 16
	s_cselect_b32 s48, s49, s48
	s_or_b32 s49, s48, 0x2000
	v_cmp_le_u32_e32 vcc, s49, v50
	s_bcnt1_i32_b64 s50, vcc
	s_cmp_ge_u32 s50, 16
	s_cselect_b32 s48, s49, s48
	s_or_b32 s49, s48, 0x1000
	v_cmp_le_u32_e32 vcc, s49, v50
	s_bcnt1_i32_b64 s50, vcc
	s_cmp_ge_u32 s50, 16
	s_cselect_b32 s48, s49, s48
	s_or_b32 s49, s48, 0x800
	v_cmp_le_u32_e32 vcc, s49, v50
	s_bcnt1_i32_b64 s50, vcc
	s_cmp_ge_u32 s50, 16
	s_cselect_b32 s48, s49, s48
	s_or_b32 s49, s48, 0x400
	v_cmp_le_u32_e32 vcc, s49, v50
	s_bcnt1_i32_b64 s50, vcc
	s_cmp_ge_u32 s50, 16
	s_cselect_b32 s48, s49, s48
	s_or_b32 s49, s48, 0x200
	v_cmp_le_u32_e32 vcc, s49, v50
	s_bcnt1_i32_b64 s50, vcc
	s_cmp_ge_u32 s50, 16
	s_cselect_b32 s48, s49, s48
	s_or_b32 s49, s48, 0x100
	v_cmp_le_u32_e32 vcc, s49, v50
	s_bcnt1_i32_b64 s50, vcc
	s_cmp_ge_u32 s50, 16
	s_cselect_b32 s48, s49, s48
	s_or_b32 s49, s48, 0x80
	v_cmp_le_u32_e32 vcc, s49, v50
	s_bcnt1_i32_b64 s50, vcc
	s_cmp_ge_u32 s50, 16
	s_cselect_b32 s48, s49, s48
	s_or_b32 s49, s48, 0x40
	v_cmp_le_u32_e32 vcc, s49, v50
	s_bcnt1_i32_b64 s50, vcc
	s_cmp_ge_u32 s50, 16
	s_cselect_b32 s48, s49, s48
	s_or_b32 s49, s48, 0x20
	v_cmp_le_u32_e32 vcc, s49, v50
	s_bcnt1_i32_b64 s50, vcc
	s_cmp_ge_u32 s50, 16
	s_cselect_b32 s48, s49, s48
	s_or_b32 s49, s48, 0x10
	v_cmp_le_u32_e32 vcc, s49, v50
	s_bcnt1_i32_b64 s50, vcc
	s_cmp_ge_u32 s50, 16
	s_cselect_b32 s48, s49, s48
	s_or_b32 s49, s48, 0x8
	v_cmp_le_u32_e32 vcc, s49, v50
	s_bcnt1_i32_b64 s50, vcc
	s_cmp_ge_u32 s50, 16
	s_cselect_b32 s48, s49, s48
	s_or_b32 s49, s48, 0x4
	v_cmp_le_u32_e32 vcc, s49, v50
	s_bcnt1_i32_b64 s50, vcc
	s_cmp_ge_u32 s50, 16
	s_cselect_b32 s48, s49, s48
	s_or_b32 s49, s48, 0x2
	v_cmp_le_u32_e32 vcc, s49, v50
	s_bcnt1_i32_b64 s50, vcc
	s_cmp_ge_u32 s50, 16
	s_cselect_b32 s48, s49, s48
	s_or_b32 s49, s48, 0x1
	v_cmp_le_u32_e32 vcc, s49, v50
	s_bcnt1_i32_b64 s50, vcc
	s_cmp_ge_u32 s50, 16
	s_cselect_b32 s48, s49, s48
	v_cmp_lt_u32_e64 s[44:45], s48, v50
	v_cmp_eq_u32_e64 s[46:47], s48, v50
	s_bcnt1_i32_b64 s50, s[44:45]
	s_sub_i32 s51, 16, s50

.La3_tk_w2:
	v_mov_b32_e32 v190, s44
	v_mov_b32_e32 v191, s45
	s_mov_b64 exec, 1
	ds_write_b64 v189, v[190:191] offset:32784
	s_mov_b64 exec, -1
	v_cndmask_b32_e64 v50, v37, v206, s[56:57]
	v_add_u32_e32 v50, 1, v50
	v_cndmask_b32_e64 v50, 0, v50, s[54:55]
	s_mov_b32 s48, 0
	s_or_b32 s49, s48, 0x40000000
	v_cmp_le_u32_e32 vcc, s49, v50
	s_bcnt1_i32_b64 s50, vcc
	s_cmp_ge_u32 s50, 16
	s_cselect_b32 s48, s49, s48
	s_or_b32 s49, s48, 0x20000000
	v_cmp_le_u32_e32 vcc, s49, v50
	s_bcnt1_i32_b64 s50, vcc
	s_cmp_ge_u32 s50, 16
	s_cselect_b32 s48, s49, s48
	s_or_b32 s49, s48, 0x10000000
	v_cmp_le_u32_e32 vcc, s49, v50
	s_bcnt1_i32_b64 s50, vcc
	s_cmp_ge_u32 s50, 16
	s_cselect_b32 s48, s49, s48
	s_or_b32 s49, s48, 0x8000000
	v_cmp_le_u32_e32 vcc, s49, v50
	s_bcnt1_i32_b64 s50, vcc
	s_cmp_ge_u32 s50, 16
	s_cselect_b32 s48, s49, s48
	s_or_b32 s49, s48, 0x4000000
	v_cmp_le_u32_e32 vcc, s49, v50
	s_bcnt1_i32_b64 s50, vcc
	s_cmp_ge_u32 s50, 16
	s_cselect_b32 s48, s49, s48
	s_or_b32 s49, s48, 0x2000000
	v_cmp_le_u32_e32 vcc, s49, v50
	s_bcnt1_i32_b64 s50, vcc
	s_cmp_ge_u32 s50, 16
	s_cselect_b32 s48, s49, s48
	s_or_b32 s49, s48, 0x1000000
	v_cmp_le_u32_e32 vcc, s49, v50
	s_bcnt1_i32_b64 s50, vcc
	s_cmp_ge_u32 s50, 16
	s_cselect_b32 s48, s49, s48
	s_or_b32 s49, s48, 0x800000
	v_cmp_le_u32_e32 vcc, s49, v50
	s_bcnt1_i32_b64 s50, vcc
	s_cmp_ge_u32 s50, 16
	s_cselect_b32 s48, s49, s48
	s_or_b32 s49, s48, 0x400000
	v_cmp_le_u32_e32 vcc, s49, v50
	s_bcnt1_i32_b64 s50, vcc
	s_cmp_ge_u32 s50, 16
	s_cselect_b32 s48, s49, s48
	s_or_b32 s49, s48, 0x200000
	v_cmp_le_u32_e32 vcc, s49, v50
	s_bcnt1_i32_b64 s50, vcc
	s_cmp_ge_u32 s50, 16
	s_cselect_b32 s48, s49, s48
	s_or_b32 s49, s48, 0x100000
	v_cmp_le_u32_e32 vcc, s49, v50
	s_bcnt1_i32_b64 s50, vcc
	s_cmp_ge_u32 s50, 16
	s_cselect_b32 s48, s49, s48
	s_or_b32 s49, s48, 0x80000
	v_cmp_le_u32_e32 vcc, s49, v50
	s_bcnt1_i32_b64 s50, vcc
	s_cmp_ge_u32 s50, 16
	s_cselect_b32 s48, s49, s48
	s_or_b32 s49, s48, 0x40000
	v_cmp_le_u32_e32 vcc, s49, v50
	s_bcnt1_i32_b64 s50, vcc
	s_cmp_ge_u32 s50, 16
	s_cselect_b32 s48, s49, s48
	s_or_b32 s49, s48, 0x20000
	v_cmp_le_u32_e32 vcc, s49, v50
	s_bcnt1_i32_b64 s50, vcc
	s_cmp_ge_u32 s50, 16
	s_cselect_b32 s48, s49, s48
	s_or_b32 s49, s48, 0x10000
	v_cmp_le_u32_e32 vcc, s49, v50
	s_bcnt1_i32_b64 s50, vcc
	s_cmp_ge_u32 s50, 16
	s_cselect_b32 s48, s49, s48
	s_or_b32 s49, s48, 0x8000
	v_cmp_le_u32_e32 vcc, s49, v50
	s_bcnt1_i32_b64 s50, vcc
	s_cmp_ge_u32 s50, 16
	s_cselect_b32 s48, s49, s48
	s_or_b32 s49, s48, 0x4000
	v_cmp_le_u32_e32 vcc, s49, v50
	s_bcnt1_i32_b64 s50, vcc
	s_cmp_ge_u32 s50, 16
	s_cselect_b32 s48, s49, s48
	s_or_b32 s49, s48, 0x2000
	v_cmp_le_u32_e32 vcc, s49, v50
	s_bcnt1_i32_b64 s50, vcc
	s_cmp_ge_u32 s50, 16
	s_cselect_b32 s48, s49, s48
	s_or_b32 s49, s48, 0x1000
	v_cmp_le_u32_e32 vcc, s49, v50
	s_bcnt1_i32_b64 s50, vcc
	s_cmp_ge_u32 s50, 16
	s_cselect_b32 s48, s49, s48
	s_or_b32 s49, s48, 0x800
	v_cmp_le_u32_e32 vcc, s49, v50
	s_bcnt1_i32_b64 s50, vcc
	s_cmp_ge_u32 s50, 16
	s_cselect_b32 s48, s49, s48
	s_or_b32 s49, s48, 0x400
	v_cmp_le_u32_e32 vcc, s49, v50
	s_bcnt1_i32_b64 s50, vcc
	s_cmp_ge_u32 s50, 16
	s_cselect_b32 s48, s49, s48
	s_or_b32 s49, s48, 0x200
	v_cmp_le_u32_e32 vcc, s49, v50
	s_bcnt1_i32_b64 s50, vcc
	s_cmp_ge_u32 s50, 16
	s_cselect_b32 s48, s49, s48
	s_or_b32 s49, s48, 0x100
	v_cmp_le_u32_e32 vcc, s49, v50
	s_bcnt1_i32_b64 s50, vcc
	s_cmp_ge_u32 s50, 16
	s_cselect_b32 s48, s49, s48
	s_or_b32 s49, s48, 0x80
	v_cmp_le_u32_e32 vcc, s49, v50
	s_bcnt1_i32_b64 s50, vcc
	s_cmp_ge_u32 s50, 16
	s_cselect_b32 s48, s49, s48
	s_or_b32 s49, s48, 0x40
	v_cmp_le_u32_e32 vcc, s49, v50
	s_bcnt1_i32_b64 s50, vcc
	s_cmp_ge_u32 s50, 16
	s_cselect_b32 s48, s49, s48
	s_or_b32 s49, s48, 0x20
	v_cmp_le_u32_e32 vcc, s49, v50
	s_bcnt1_i32_b64 s50, vcc
	s_cmp_ge_u32 s50, 16
	s_cselect_b32 s48, s49, s48
	s_or_b32 s49, s48, 0x10
	v_cmp_le_u32_e32 vcc, s49, v50
	s_bcnt1_i32_b64 s50, vcc
	s_cmp_ge_u32 s50, 16
	s_cselect_b32 s48, s49, s48
	s_or_b32 s49, s48, 0x8
	v_cmp_le_u32_e32 vcc, s49, v50
	s_bcnt1_i32_b64 s50, vcc
	s_cmp_ge_u32 s50, 16
	s_cselect_b32 s48, s49, s48
	s_or_b32 s49, s48, 0x4
	v_cmp_le_u32_e32 vcc, s49, v50
	s_bcnt1_i32_b64 s50, vcc
	s_cmp_ge_u32 s50, 16
	s_cselect_b32 s48, s49, s48
	s_or_b32 s49, s48, 0x2
	v_cmp_le_u32_e32 vcc, s49, v50
	s_bcnt1_i32_b64 s50, vcc
	s_cmp_ge_u32 s50, 16
	s_cselect_b32 s48, s49, s48
	s_or_b32 s49, s48, 0x1
	v_cmp_le_u32_e32 vcc, s49, v50
	s_bcnt1_i32_b64 s50, vcc
	s_cmp_ge_u32 s50, 16
	s_cselect_b32 s48, s49, s48
	v_cmp_lt_u32_e64 s[44:45], s48, v50
	v_cmp_eq_u32_e64 s[46:47], s48, v50
	s_bcnt1_i32_b64 s50, s[44:45]
	s_sub_i32 s51, 16, s50

.La3_tk_w3:
	v_mov_b32_e32 v190, s44
	v_mov_b32_e32 v191, s45
	s_mov_b64 exec, 1
	ds_write_b64 v189, v[190:191] offset:32792
	s_mov_b64 exec, -1
	v_cndmask_b32_e64 v50, v38, v206, s[56:57]
	v_add_u32_e32 v50, 1, v50
	v_cndmask_b32_e64 v50, 0, v50, s[54:55]
	s_mov_b32 s48, 0
	s_or_b32 s49, s48, 0x40000000
	v_cmp_le_u32_e32 vcc, s49, v50
	s_bcnt1_i32_b64 s50, vcc
	s_cmp_ge_u32 s50, 16
	s_cselect_b32 s48, s49, s48
	s_or_b32 s49, s48, 0x20000000
	v_cmp_le_u32_e32 vcc, s49, v50
	s_bcnt1_i32_b64 s50, vcc
	s_cmp_ge_u32 s50, 16
	s_cselect_b32 s48, s49, s48
	s_or_b32 s49, s48, 0x10000000
	v_cmp_le_u32_e32 vcc, s49, v50
	s_bcnt1_i32_b64 s50, vcc
	s_cmp_ge_u32 s50, 16
	s_cselect_b32 s48, s49, s48
	s_or_b32 s49, s48, 0x8000000
	v_cmp_le_u32_e32 vcc, s49, v50
	s_bcnt1_i32_b64 s50, vcc
	s_cmp_ge_u32 s50, 16
	s_cselect_b32 s48, s49, s48
	s_or_b32 s49, s48, 0x4000000
	v_cmp_le_u32_e32 vcc, s49, v50
	s_bcnt1_i32_b64 s50, vcc
	s_cmp_ge_u32 s50, 16
	s_cselect_b32 s48, s49, s48
	s_or_b32 s49, s48, 0x2000000
	v_cmp_le_u32_e32 vcc, s49, v50
	s_bcnt1_i32_b64 s50, vcc
	s_cmp_ge_u32 s50, 16
	s_cselect_b32 s48, s49, s48
	s_or_b32 s49, s48, 0x1000000
	v_cmp_le_u32_e32 vcc, s49, v50
	s_bcnt1_i32_b64 s50, vcc
	s_cmp_ge_u32 s50, 16
	s_cselect_b32 s48, s49, s48
	s_or_b32 s49, s48, 0x800000
	v_cmp_le_u32_e32 vcc, s49, v50
	s_bcnt1_i32_b64 s50, vcc
	s_cmp_ge_u32 s50, 16
	s_cselect_b32 s48, s49, s48
	s_or_b32 s49, s48, 0x400000
	v_cmp_le_u32_e32 vcc, s49, v50
	s_bcnt1_i32_b64 s50, vcc
	s_cmp_ge_u32 s50, 16
	s_cselect_b32 s48, s49, s48
	s_or_b32 s49, s48, 0x200000
	v_cmp_le_u32_e32 vcc, s49, v50
	s_bcnt1_i32_b64 s50, vcc
	s_cmp_ge_u32 s50, 16
	s_cselect_b32 s48, s49, s48
	s_or_b32 s49, s48, 0x100000
	v_cmp_le_u32_e32 vcc, s49, v50
	s_bcnt1_i32_b64 s50, vcc
	s_cmp_ge_u32 s50, 16
	s_cselect_b32 s48, s49, s48
	s_or_b32 s49, s48, 0x80000
	v_cmp_le_u32_e32 vcc, s49, v50
	s_bcnt1_i32_b64 s50, vcc
	s_cmp_ge_u32 s50, 16
	s_cselect_b32 s48, s49, s48
	s_or_b32 s49, s48, 0x40000
	v_cmp_le_u32_e32 vcc, s49, v50
	s_bcnt1_i32_b64 s50, vcc
	s_cmp_ge_u32 s50, 16
	s_cselect_b32 s48, s49, s48
	s_or_b32 s49, s48, 0x20000
	v_cmp_le_u32_e32 vcc, s49, v50
	s_bcnt1_i32_b64 s50, vcc
	s_cmp_ge_u32 s50, 16
	s_cselect_b32 s48, s49, s48
	s_or_b32 s49, s48, 0x10000
	v_cmp_le_u32_e32 vcc, s49, v50
	s_bcnt1_i32_b64 s50, vcc
	s_cmp_ge_u32 s50, 16
	s_cselect_b32 s48, s49, s48
	s_or_b32 s49, s48, 0x8000
	v_cmp_le_u32_e32 vcc, s49, v50
	s_bcnt1_i32_b64 s50, vcc
	s_cmp_ge_u32 s50, 16
	s_cselect_b32 s48, s49, s48
	s_or_b32 s49, s48, 0x4000
	v_cmp_le_u32_e32 vcc, s49, v50
	s_bcnt1_i32_b64 s50, vcc
	s_cmp_ge_u32 s50, 16
	s_cselect_b32 s48, s49, s48
	s_or_b32 s49, s48, 0x2000
	v_cmp_le_u32_e32 vcc, s49, v50
	s_bcnt1_i32_b64 s50, vcc
	s_cmp_ge_u32 s50, 16
	s_cselect_b32 s48, s49, s48
	s_or_b32 s49, s48, 0x1000
	v_cmp_le_u32_e32 vcc, s49, v50
	s_bcnt1_i32_b64 s50, vcc
	s_cmp_ge_u32 s50, 16
	s_cselect_b32 s48, s49, s48
	s_or_b32 s49, s48, 0x800
	v_cmp_le_u32_e32 vcc, s49, v50
	s_bcnt1_i32_b64 s50, vcc
	s_cmp_ge_u32 s50, 16
	s_cselect_b32 s48, s49, s48
	s_or_b32 s49, s48, 0x400
	v_cmp_le_u32_e32 vcc, s49, v50
	s_bcnt1_i32_b64 s50, vcc
	s_cmp_ge_u32 s50, 16
	s_cselect_b32 s48, s49, s48
	s_or_b32 s49, s48, 0x200
	v_cmp_le_u32_e32 vcc, s49, v50
	s_bcnt1_i32_b64 s50, vcc
	s_cmp_ge_u32 s50, 16
	s_cselect_b32 s48, s49, s48
	s_or_b32 s49, s48, 0x100
	v_cmp_le_u32_e32 vcc, s49, v50
	s_bcnt1_i32_b64 s50, vcc
	s_cmp_ge_u32 s50, 16
	s_cselect_b32 s48, s49, s48
	s_or_b32 s49, s48, 0x80
	v_cmp_le_u32_e32 vcc, s49, v50
	s_bcnt1_i32_b64 s50, vcc
	s_cmp_ge_u32 s50, 16
	s_cselect_b32 s48, s49, s48
	s_or_b32 s49, s48, 0x40
	v_cmp_le_u32_e32 vcc, s49, v50
	s_bcnt1_i32_b64 s50, vcc
	s_cmp_ge_u32 s50, 16
	s_cselect_b32 s48, s49, s48
	s_or_b32 s49, s48, 0x20
	v_cmp_le_u32_e32 vcc, s49, v50
	s_bcnt1_i32_b64 s50, vcc
	s_cmp_ge_u32 s50, 16
	s_cselect_b32 s48, s49, s48
	s_or_b32 s49, s48, 0x10
	v_cmp_le_u32_e32 vcc, s49, v50
	s_bcnt1_i32_b64 s50, vcc
	s_cmp_ge_u32 s50, 16
	s_cselect_b32 s48, s49, s48
	s_or_b32 s49, s48, 0x8
	v_cmp_le_u32_e32 vcc, s49, v50
	s_bcnt1_i32_b64 s50, vcc
	s_cmp_ge_u32 s50, 16
	s_cselect_b32 s48, s49, s48
	s_or_b32 s49, s48, 0x4
	v_cmp_le_u32_e32 vcc, s49, v50
	s_bcnt1_i32_b64 s50, vcc
	s_cmp_ge_u32 s50, 16
	s_cselect_b32 s48, s49, s48
	s_or_b32 s49, s48, 0x2
	v_cmp_le_u32_e32 vcc, s49, v50
	s_bcnt1_i32_b64 s50, vcc
	s_cmp_ge_u32 s50, 16
	s_cselect_b32 s48, s49, s48
	s_or_b32 s49, s48, 0x1
	v_cmp_le_u32_e32 vcc, s49, v50
	s_bcnt1_i32_b64 s50, vcc
	s_cmp_ge_u32 s50, 16
	s_cselect_b32 s48, s49, s48
	v_cmp_lt_u32_e64 s[44:45], s48, v50
	v_cmp_eq_u32_e64 s[46:47], s48, v50
	s_bcnt1_i32_b64 s50, s[44:45]
	s_sub_i32 s51, 16, s50

.La3_tk_w4:
	v_mov_b32_e32 v190, s44
	v_mov_b32_e32 v191, s45
	s_mov_b64 exec, 1
	ds_write_b64 v189, v[190:191] offset:32800
	s_mov_b64 exec, -1
	v_cndmask_b32_e64 v50, v39, v206, s[56:57]
	v_add_u32_e32 v50, 1, v50
	v_cndmask_b32_e64 v50, 0, v50, s[54:55]
	s_mov_b32 s48, 0
	s_or_b32 s49, s48, 0x40000000
	v_cmp_le_u32_e32 vcc, s49, v50
	s_bcnt1_i32_b64 s50, vcc
	s_cmp_ge_u32 s50, 16
	s_cselect_b32 s48, s49, s48
	s_or_b32 s49, s48, 0x20000000
	v_cmp_le_u32_e32 vcc, s49, v50
	s_bcnt1_i32_b64 s50, vcc
	s_cmp_ge_u32 s50, 16
	s_cselect_b32 s48, s49, s48
	s_or_b32 s49, s48, 0x10000000
	v_cmp_le_u32_e32 vcc, s49, v50
	s_bcnt1_i32_b64 s50, vcc
	s_cmp_ge_u32 s50, 16
	s_cselect_b32 s48, s49, s48
	s_or_b32 s49, s48, 0x8000000
	v_cmp_le_u32_e32 vcc, s49, v50
	s_bcnt1_i32_b64 s50, vcc
	s_cmp_ge_u32 s50, 16
	s_cselect_b32 s48, s49, s48
	s_or_b32 s49, s48, 0x4000000
	v_cmp_le_u32_e32 vcc, s49, v50
	s_bcnt1_i32_b64 s50, vcc
	s_cmp_ge_u32 s50, 16
	s_cselect_b32 s48, s49, s48
	s_or_b32 s49, s48, 0x2000000
	v_cmp_le_u32_e32 vcc, s49, v50
	s_bcnt1_i32_b64 s50, vcc
	s_cmp_ge_u32 s50, 16
	s_cselect_b32 s48, s49, s48
	s_or_b32 s49, s48, 0x1000000
	v_cmp_le_u32_e32 vcc, s49, v50
	s_bcnt1_i32_b64 s50, vcc
	s_cmp_ge_u32 s50, 16
	s_cselect_b32 s48, s49, s48
	s_or_b32 s49, s48, 0x800000
	v_cmp_le_u32_e32 vcc, s49, v50
	s_bcnt1_i32_b64 s50, vcc
	s_cmp_ge_u32 s50, 16
	s_cselect_b32 s48, s49, s48
	s_or_b32 s49, s48, 0x400000
	v_cmp_le_u32_e32 vcc, s49, v50
	s_bcnt1_i32_b64 s50, vcc
	s_cmp_ge_u32 s50, 16
	s_cselect_b32 s48, s49, s48
	s_or_b32 s49, s48, 0x200000
	v_cmp_le_u32_e32 vcc, s49, v50
	s_bcnt1_i32_b64 s50, vcc
	s_cmp_ge_u32 s50, 16
	s_cselect_b32 s48, s49, s48
	s_or_b32 s49, s48, 0x100000
	v_cmp_le_u32_e32 vcc, s49, v50
	s_bcnt1_i32_b64 s50, vcc
	s_cmp_ge_u32 s50, 16
	s_cselect_b32 s48, s49, s48
	s_or_b32 s49, s48, 0x80000
	v_cmp_le_u32_e32 vcc, s49, v50
	s_bcnt1_i32_b64 s50, vcc
	s_cmp_ge_u32 s50, 16
	s_cselect_b32 s48, s49, s48
	s_or_b32 s49, s48, 0x40000
	v_cmp_le_u32_e32 vcc, s49, v50
	s_bcnt1_i32_b64 s50, vcc
	s_cmp_ge_u32 s50, 16
	s_cselect_b32 s48, s49, s48
	s_or_b32 s49, s48, 0x20000
	v_cmp_le_u32_e32 vcc, s49, v50
	s_bcnt1_i32_b64 s50, vcc
	s_cmp_ge_u32 s50, 16
	s_cselect_b32 s48, s49, s48
	s_or_b32 s49, s48, 0x10000
	v_cmp_le_u32_e32 vcc, s49, v50
	s_bcnt1_i32_b64 s50, vcc
	s_cmp_ge_u32 s50, 16
	s_cselect_b32 s48, s49, s48
	s_or_b32 s49, s48, 0x8000
	v_cmp_le_u32_e32 vcc, s49, v50
	s_bcnt1_i32_b64 s50, vcc
	s_cmp_ge_u32 s50, 16
	s_cselect_b32 s48, s49, s48
	s_or_b32 s49, s48, 0x4000
	v_cmp_le_u32_e32 vcc, s49, v50
	s_bcnt1_i32_b64 s50, vcc
	s_cmp_ge_u32 s50, 16
	s_cselect_b32 s48, s49, s48
	s_or_b32 s49, s48, 0x2000
	v_cmp_le_u32_e32 vcc, s49, v50
	s_bcnt1_i32_b64 s50, vcc
	s_cmp_ge_u32 s50, 16
	s_cselect_b32 s48, s49, s48
	s_or_b32 s49, s48, 0x1000
	v_cmp_le_u32_e32 vcc, s49, v50
	s_bcnt1_i32_b64 s50, vcc
	s_cmp_ge_u32 s50, 16
	s_cselect_b32 s48, s49, s48
	s_or_b32 s49, s48, 0x800
	v_cmp_le_u32_e32 vcc, s49, v50
	s_bcnt1_i32_b64 s50, vcc
	s_cmp_ge_u32 s50, 16
	s_cselect_b32 s48, s49, s48
	s_or_b32 s49, s48, 0x400
	v_cmp_le_u32_e32 vcc, s49, v50
	s_bcnt1_i32_b64 s50, vcc
	s_cmp_ge_u32 s50, 16
	s_cselect_b32 s48, s49, s48
	s_or_b32 s49, s48, 0x200
	v_cmp_le_u32_e32 vcc, s49, v50
	s_bcnt1_i32_b64 s50, vcc
	s_cmp_ge_u32 s50, 16
	s_cselect_b32 s48, s49, s48
	s_or_b32 s49, s48, 0x100
	v_cmp_le_u32_e32 vcc, s49, v50
	s_bcnt1_i32_b64 s50, vcc
	s_cmp_ge_u32 s50, 16
	s_cselect_b32 s48, s49, s48
	s_or_b32 s49, s48, 0x80
	v_cmp_le_u32_e32 vcc, s49, v50
	s_bcnt1_i32_b64 s50, vcc
	s_cmp_ge_u32 s50, 16
	s_cselect_b32 s48, s49, s48
	s_or_b32 s49, s48, 0x40
	v_cmp_le_u32_e32 vcc, s49, v50
	s_bcnt1_i32_b64 s50, vcc
	s_cmp_ge_u32 s50, 16
	s_cselect_b32 s48, s49, s48
	s_or_b32 s49, s48, 0x20
	v_cmp_le_u32_e32 vcc, s49, v50
	s_bcnt1_i32_b64 s50, vcc
	s_cmp_ge_u32 s50, 16
	s_cselect_b32 s48, s49, s48
	s_or_b32 s49, s48, 0x10
	v_cmp_le_u32_e32 vcc, s49, v50
	s_bcnt1_i32_b64 s50, vcc
	s_cmp_ge_u32 s50, 16
	s_cselect_b32 s48, s49, s48
	s_or_b32 s49, s48, 0x8
	v_cmp_le_u32_e32 vcc, s49, v50
	s_bcnt1_i32_b64 s50, vcc
	s_cmp_ge_u32 s50, 16
	s_cselect_b32 s48, s49, s48
	s_or_b32 s49, s48, 0x4
	v_cmp_le_u32_e32 vcc, s49, v50
	s_bcnt1_i32_b64 s50, vcc
	s_cmp_ge_u32 s50, 16
	s_cselect_b32 s48, s49, s48
	s_or_b32 s49, s48, 0x2
	v_cmp_le_u32_e32 vcc, s49, v50
	s_bcnt1_i32_b64 s50, vcc
	s_cmp_ge_u32 s50, 16
	s_cselect_b32 s48, s49, s48
	s_or_b32 s49, s48, 0x1
	v_cmp_le_u32_e32 vcc, s49, v50
	s_bcnt1_i32_b64 s50, vcc
	s_cmp_ge_u32 s50, 16
	s_cselect_b32 s48, s49, s48
	v_cmp_lt_u32_e64 s[44:45], s48, v50
	v_cmp_eq_u32_e64 s[46:47], s48, v50
	s_bcnt1_i32_b64 s50, s[44:45]
	s_sub_i32 s51, 16, s50

.La3_tk_w5:
	v_mov_b32_e32 v190, s44
	v_mov_b32_e32 v191, s45
	s_mov_b64 exec, 1
	ds_write_b64 v189, v[190:191] offset:32808
	s_mov_b64 exec, -1
	v_cndmask_b32_e64 v50, v40, v206, s[56:57]
	v_add_u32_e32 v50, 1, v50
	v_cndmask_b32_e64 v50, 0, v50, s[54:55]
	s_mov_b32 s48, 0
	s_or_b32 s49, s48, 0x40000000
	v_cmp_le_u32_e32 vcc, s49, v50
	s_bcnt1_i32_b64 s50, vcc
	s_cmp_ge_u32 s50, 16
	s_cselect_b32 s48, s49, s48
	s_or_b32 s49, s48, 0x20000000
	v_cmp_le_u32_e32 vcc, s49, v50
	s_bcnt1_i32_b64 s50, vcc
	s_cmp_ge_u32 s50, 16
	s_cselect_b32 s48, s49, s48
	s_or_b32 s49, s48, 0x10000000
	v_cmp_le_u32_e32 vcc, s49, v50
	s_bcnt1_i32_b64 s50, vcc
	s_cmp_ge_u32 s50, 16
	s_cselect_b32 s48, s49, s48
	s_or_b32 s49, s48, 0x8000000
	v_cmp_le_u32_e32 vcc, s49, v50
	s_bcnt1_i32_b64 s50, vcc
	s_cmp_ge_u32 s50, 16
	s_cselect_b32 s48, s49, s48
	s_or_b32 s49, s48, 0x4000000
	v_cmp_le_u32_e32 vcc, s49, v50
	s_bcnt1_i32_b64 s50, vcc
	s_cmp_ge_u32 s50, 16
	s_cselect_b32 s48, s49, s48
	s_or_b32 s49, s48, 0x2000000
	v_cmp_le_u32_e32 vcc, s49, v50
	s_bcnt1_i32_b64 s50, vcc
	s_cmp_ge_u32 s50, 16
	s_cselect_b32 s48, s49, s48
	s_or_b32 s49, s48, 0x1000000
	v_cmp_le_u32_e32 vcc, s49, v50
	s_bcnt1_i32_b64 s50, vcc
	s_cmp_ge_u32 s50, 16
	s_cselect_b32 s48, s49, s48
	s_or_b32 s49, s48, 0x800000
	v_cmp_le_u32_e32 vcc, s49, v50
	s_bcnt1_i32_b64 s50, vcc
	s_cmp_ge_u32 s50, 16
	s_cselect_b32 s48, s49, s48
	s_or_b32 s49, s48, 0x400000
	v_cmp_le_u32_e32 vcc, s49, v50
	s_bcnt1_i32_b64 s50, vcc
	s_cmp_ge_u32 s50, 16
	s_cselect_b32 s48, s49, s48
	s_or_b32 s49, s48, 0x200000
	v_cmp_le_u32_e32 vcc, s49, v50
	s_bcnt1_i32_b64 s50, vcc
	s_cmp_ge_u32 s50, 16
	s_cselect_b32 s48, s49, s48
	s_or_b32 s49, s48, 0x100000
	v_cmp_le_u32_e32 vcc, s49, v50
	s_bcnt1_i32_b64 s50, vcc
	s_cmp_ge_u32 s50, 16
	s_cselect_b32 s48, s49, s48
	s_or_b32 s49, s48, 0x80000
	v_cmp_le_u32_e32 vcc, s49, v50
	s_bcnt1_i32_b64 s50, vcc
	s_cmp_ge_u32 s50, 16
	s_cselect_b32 s48, s49, s48
	s_or_b32 s49, s48, 0x40000
	v_cmp_le_u32_e32 vcc, s49, v50
	s_bcnt1_i32_b64 s50, vcc
	s_cmp_ge_u32 s50, 16
	s_cselect_b32 s48, s49, s48
	s_or_b32 s49, s48, 0x20000
	v_cmp_le_u32_e32 vcc, s49, v50
	s_bcnt1_i32_b64 s50, vcc
	s_cmp_ge_u32 s50, 16
	s_cselect_b32 s48, s49, s48
	s_or_b32 s49, s48, 0x10000
	v_cmp_le_u32_e32 vcc, s49, v50
	s_bcnt1_i32_b64 s50, vcc
	s_cmp_ge_u32 s50, 16
	s_cselect_b32 s48, s49, s48
	s_or_b32 s49, s48, 0x8000
	v_cmp_le_u32_e32 vcc, s49, v50
	s_bcnt1_i32_b64 s50, vcc
	s_cmp_ge_u32 s50, 16
	s_cselect_b32 s48, s49, s48
	s_or_b32 s49, s48, 0x4000
	v_cmp_le_u32_e32 vcc, s49, v50
	s_bcnt1_i32_b64 s50, vcc
	s_cmp_ge_u32 s50, 16
	s_cselect_b32 s48, s49, s48
	s_or_b32 s49, s48, 0x2000
	v_cmp_le_u32_e32 vcc, s49, v50
	s_bcnt1_i32_b64 s50, vcc
	s_cmp_ge_u32 s50, 16
	s_cselect_b32 s48, s49, s48
	s_or_b32 s49, s48, 0x1000
	v_cmp_le_u32_e32 vcc, s49, v50
	s_bcnt1_i32_b64 s50, vcc
	s_cmp_ge_u32 s50, 16
	s_cselect_b32 s48, s49, s48
	s_or_b32 s49, s48, 0x800
	v_cmp_le_u32_e32 vcc, s49, v50
	s_bcnt1_i32_b64 s50, vcc
	s_cmp_ge_u32 s50, 16
	s_cselect_b32 s48, s49, s48
	s_or_b32 s49, s48, 0x400
	v_cmp_le_u32_e32 vcc, s49, v50
	s_bcnt1_i32_b64 s50, vcc
	s_cmp_ge_u32 s50, 16
	s_cselect_b32 s48, s49, s48
	s_or_b32 s49, s48, 0x200
	v_cmp_le_u32_e32 vcc, s49, v50
	s_bcnt1_i32_b64 s50, vcc
	s_cmp_ge_u32 s50, 16
	s_cselect_b32 s48, s49, s48
	s_or_b32 s49, s48, 0x100
	v_cmp_le_u32_e32 vcc, s49, v50
	s_bcnt1_i32_b64 s50, vcc
	s_cmp_ge_u32 s50, 16
	s_cselect_b32 s48, s49, s48
	s_or_b32 s49, s48, 0x80
	v_cmp_le_u32_e32 vcc, s49, v50
	s_bcnt1_i32_b64 s50, vcc
	s_cmp_ge_u32 s50, 16
	s_cselect_b32 s48, s49, s48
	s_or_b32 s49, s48, 0x40
	v_cmp_le_u32_e32 vcc, s49, v50
	s_bcnt1_i32_b64 s50, vcc
	s_cmp_ge_u32 s50, 16
	s_cselect_b32 s48, s49, s48
	s_or_b32 s49, s48, 0x20
	v_cmp_le_u32_e32 vcc, s49, v50
	s_bcnt1_i32_b64 s50, vcc
	s_cmp_ge_u32 s50, 16
	s_cselect_b32 s48, s49, s48
	s_or_b32 s49, s48, 0x10
	v_cmp_le_u32_e32 vcc, s49, v50
	s_bcnt1_i32_b64 s50, vcc
	s_cmp_ge_u32 s50, 16
	s_cselect_b32 s48, s49, s48
	s_or_b32 s49, s48, 0x8
	v_cmp_le_u32_e32 vcc, s49, v50
	s_bcnt1_i32_b64 s50, vcc
	s_cmp_ge_u32 s50, 16
	s_cselect_b32 s48, s49, s48
	s_or_b32 s49, s48, 0x4
	v_cmp_le_u32_e32 vcc, s49, v50
	s_bcnt1_i32_b64 s50, vcc
	s_cmp_ge_u32 s50, 16
	s_cselect_b32 s48, s49, s48
	s_or_b32 s49, s48, 0x2
	v_cmp_le_u32_e32 vcc, s49, v50
	s_bcnt1_i32_b64 s50, vcc
	s_cmp_ge_u32 s50, 16
	s_cselect_b32 s48, s49, s48
	s_or_b32 s49, s48, 0x1
	v_cmp_le_u32_e32 vcc, s49, v50
	s_bcnt1_i32_b64 s50, vcc
	s_cmp_ge_u32 s50, 16
	s_cselect_b32 s48, s49, s48
	v_cmp_lt_u32_e64 s[44:45], s48, v50
	v_cmp_eq_u32_e64 s[46:47], s48, v50
	s_bcnt1_i32_b64 s50, s[44:45]
	s_sub_i32 s51, 16, s50

.La3_tk_w6:
	v_mov_b32_e32 v190, s44
	v_mov_b32_e32 v191, s45
	s_mov_b64 exec, 1
	ds_write_b64 v189, v[190:191] offset:32816
	s_mov_b64 exec, -1
	v_cndmask_b32_e64 v50, v41, v206, s[56:57]
	v_add_u32_e32 v50, 1, v50
	v_cndmask_b32_e64 v50, 0, v50, s[54:55]
	s_mov_b32 s48, 0
	s_or_b32 s49, s48, 0x40000000
	v_cmp_le_u32_e32 vcc, s49, v50
	s_bcnt1_i32_b64 s50, vcc
	s_cmp_ge_u32 s50, 16
	s_cselect_b32 s48, s49, s48
	s_or_b32 s49, s48, 0x20000000
	v_cmp_le_u32_e32 vcc, s49, v50
	s_bcnt1_i32_b64 s50, vcc
	s_cmp_ge_u32 s50, 16
	s_cselect_b32 s48, s49, s48
	s_or_b32 s49, s48, 0x10000000
	v_cmp_le_u32_e32 vcc, s49, v50
	s_bcnt1_i32_b64 s50, vcc
	s_cmp_ge_u32 s50, 16
	s_cselect_b32 s48, s49, s48
	s_or_b32 s49, s48, 0x8000000
	v_cmp_le_u32_e32 vcc, s49, v50
	s_bcnt1_i32_b64 s50, vcc
	s_cmp_ge_u32 s50, 16
	s_cselect_b32 s48, s49, s48
	s_or_b32 s49, s48, 0x4000000
	v_cmp_le_u32_e32 vcc, s49, v50
	s_bcnt1_i32_b64 s50, vcc
	s_cmp_ge_u32 s50, 16
	s_cselect_b32 s48, s49, s48
	s_or_b32 s49, s48, 0x2000000
	v_cmp_le_u32_e32 vcc, s49, v50
	s_bcnt1_i32_b64 s50, vcc
	s_cmp_ge_u32 s50, 16
	s_cselect_b32 s48, s49, s48
	s_or_b32 s49, s48, 0x1000000
	v_cmp_le_u32_e32 vcc, s49, v50
	s_bcnt1_i32_b64 s50, vcc
	s_cmp_ge_u32 s50, 16
	s_cselect_b32 s48, s49, s48
	s_or_b32 s49, s48, 0x800000
	v_cmp_le_u32_e32 vcc, s49, v50
	s_bcnt1_i32_b64 s50, vcc
	s_cmp_ge_u32 s50, 16
	s_cselect_b32 s48, s49, s48
	s_or_b32 s49, s48, 0x400000
	v_cmp_le_u32_e32 vcc, s49, v50
	s_bcnt1_i32_b64 s50, vcc
	s_cmp_ge_u32 s50, 16
	s_cselect_b32 s48, s49, s48
	s_or_b32 s49, s48, 0x200000
	v_cmp_le_u32_e32 vcc, s49, v50
	s_bcnt1_i32_b64 s50, vcc
	s_cmp_ge_u32 s50, 16
	s_cselect_b32 s48, s49, s48
	s_or_b32 s49, s48, 0x100000
	v_cmp_le_u32_e32 vcc, s49, v50
	s_bcnt1_i32_b64 s50, vcc
	s_cmp_ge_u32 s50, 16
	s_cselect_b32 s48, s49, s48
	s_or_b32 s49, s48, 0x80000
	v_cmp_le_u32_e32 vcc, s49, v50
	s_bcnt1_i32_b64 s50, vcc
	s_cmp_ge_u32 s50, 16
	s_cselect_b32 s48, s49, s48
	s_or_b32 s49, s48, 0x40000
	v_cmp_le_u32_e32 vcc, s49, v50
	s_bcnt1_i32_b64 s50, vcc
	s_cmp_ge_u32 s50, 16
	s_cselect_b32 s48, s49, s48
	s_or_b32 s49, s48, 0x20000
	v_cmp_le_u32_e32 vcc, s49, v50
	s_bcnt1_i32_b64 s50, vcc
	s_cmp_ge_u32 s50, 16
	s_cselect_b32 s48, s49, s48
	s_or_b32 s49, s48, 0x10000
	v_cmp_le_u32_e32 vcc, s49, v50
	s_bcnt1_i32_b64 s50, vcc
	s_cmp_ge_u32 s50, 16
	s_cselect_b32 s48, s49, s48
	s_or_b32 s49, s48, 0x8000
	v_cmp_le_u32_e32 vcc, s49, v50
	s_bcnt1_i32_b64 s50, vcc
	s_cmp_ge_u32 s50, 16
	s_cselect_b32 s48, s49, s48
	s_or_b32 s49, s48, 0x4000
	v_cmp_le_u32_e32 vcc, s49, v50
	s_bcnt1_i32_b64 s50, vcc
	s_cmp_ge_u32 s50, 16
	s_cselect_b32 s48, s49, s48
	s_or_b32 s49, s48, 0x2000
	v_cmp_le_u32_e32 vcc, s49, v50
	s_bcnt1_i32_b64 s50, vcc
	s_cmp_ge_u32 s50, 16
	s_cselect_b32 s48, s49, s48
	s_or_b32 s49, s48, 0x1000
	v_cmp_le_u32_e32 vcc, s49, v50
	s_bcnt1_i32_b64 s50, vcc
	s_cmp_ge_u32 s50, 16
	s_cselect_b32 s48, s49, s48
	s_or_b32 s49, s48, 0x800
	v_cmp_le_u32_e32 vcc, s49, v50
	s_bcnt1_i32_b64 s50, vcc
	s_cmp_ge_u32 s50, 16
	s_cselect_b32 s48, s49, s48
	s_or_b32 s49, s48, 0x400
	v_cmp_le_u32_e32 vcc, s49, v50
	s_bcnt1_i32_b64 s50, vcc
	s_cmp_ge_u32 s50, 16
	s_cselect_b32 s48, s49, s48
	s_or_b32 s49, s48, 0x200
	v_cmp_le_u32_e32 vcc, s49, v50
	s_bcnt1_i32_b64 s50, vcc
	s_cmp_ge_u32 s50, 16
	s_cselect_b32 s48, s49, s48
	s_or_b32 s49, s48, 0x100
	v_cmp_le_u32_e32 vcc, s49, v50
	s_bcnt1_i32_b64 s50, vcc
	s_cmp_ge_u32 s50, 16
	s_cselect_b32 s48, s49, s48
	s_or_b32 s49, s48, 0x80
	v_cmp_le_u32_e32 vcc, s49, v50
	s_bcnt1_i32_b64 s50, vcc
	s_cmp_ge_u32 s50, 16
	s_cselect_b32 s48, s49, s48
	s_or_b32 s49, s48, 0x40
	v_cmp_le_u32_e32 vcc, s49, v50
	s_bcnt1_i32_b64 s50, vcc
	s_cmp_ge_u32 s50, 16
	s_cselect_b32 s48, s49, s48
	s_or_b32 s49, s48, 0x20
	v_cmp_le_u32_e32 vcc, s49, v50
	s_bcnt1_i32_b64 s50, vcc
	s_cmp_ge_u32 s50, 16
	s_cselect_b32 s48, s49, s48
	s_or_b32 s49, s48, 0x10
	v_cmp_le_u32_e32 vcc, s49, v50
	s_bcnt1_i32_b64 s50, vcc
	s_cmp_ge_u32 s50, 16
	s_cselect_b32 s48, s49, s48
	s_or_b32 s49, s48, 0x8
	v_cmp_le_u32_e32 vcc, s49, v50
	s_bcnt1_i32_b64 s50, vcc
	s_cmp_ge_u32 s50, 16
	s_cselect_b32 s48, s49, s48
	s_or_b32 s49, s48, 0x4
	v_cmp_le_u32_e32 vcc, s49, v50
	s_bcnt1_i32_b64 s50, vcc
	s_cmp_ge_u32 s50, 16
	s_cselect_b32 s48, s49, s48
	s_or_b32 s49, s48, 0x2
	v_cmp_le_u32_e32 vcc, s49, v50
	s_bcnt1_i32_b64 s50, vcc
	s_cmp_ge_u32 s50, 16
	s_cselect_b32 s48, s49, s48
	s_or_b32 s49, s48, 0x1
	v_cmp_le_u32_e32 vcc, s49, v50
	s_bcnt1_i32_b64 s50, vcc
	s_cmp_ge_u32 s50, 16
	s_cselect_b32 s48, s49, s48
	v_cmp_lt_u32_e64 s[44:45], s48, v50
	v_cmp_eq_u32_e64 s[46:47], s48, v50
	s_bcnt1_i32_b64 s50, s[44:45]
	s_sub_i32 s51, 16, s50

.La3_tk_w7:
	v_mov_b32_e32 v190, s44
	v_mov_b32_e32 v191, s45
	s_mov_b64 exec, 1
	ds_write_b64 v189, v[190:191] offset:32824
	s_mov_b64 exec, -1
.La3_tk_done:
	s_waitcnt lgkmcnt(0)
	s_barrier
	v_and_b32_e32 v212, 15, v163
	v_bfe_u32 v213, v163, 4, 2
	v_readlane_b32 s52, v236, 41
	v_readlane_b32 s53, v236, 42
	s_lshl_b32 s28, s8, 7
	s_add_u32 s52, s52, s28
	s_addc_u32 s53, s53, 0
	v_add_u32_e32 v190, s9, v212
	v_lshlrev_b32_e32 v191, 10, v190
	v_lshl_add_u32 v191, v213, 4, v191
	v_add_u32_e32 v206, 0x4000, v191
	global_load_dwordx4 v[98:101], v191, s[52:53]
	global_load_dwordx4 v[102:105], v191, s[52:53] offset:64
	global_load_dwordx4 v[106:109], v206, s[52:53]
	global_load_dwordx4 v[110:113], v206, s[52:53] offset:64
	v_readlane_b32 s36, v236, 31
	v_readlane_b32 s37, v236, 32
	s_mul_i32 s28, s8, 6
	s_add_i32 s28, s28, 0x3200
	s_add_u32 s36, s36, s28
	s_addc_u32 s37, s37, 0
	v_mul_u32_u24_e32 v207, 0x3300, v190
	v_add_u32_e32 v208, 0x33000, v207
	global_load_ushort v160, v207, s[36:37] offset:2
	global_load_ushort v182, v207, s[36:37] offset:4
	global_load_ushort v161, v208, s[36:37] offset:2
	global_load_ushort v183, v208, s[36:37] offset:4
	v_readlane_b32 s38, v236, 39
	v_readlane_b32 s39, v236, 40
	s_lshl_b32 s28, s8, 7
	s_add_u32 s38, s38, s28
	s_addc_u32 s39, s39, 0
	v_mul_u32_u24_e32 v184, 0x480, v190
	v_lshl_add_u32 v184, v213, 3, v184
	v_add_u32_e32 v185, 0x4800, v184
	v_lshlrev_b32_e32 v209, 3, v212
	ds_read_b64 v[154:155], v209 offset:32768
	ds_read_b64 v[156:157], v209 offset:32896
	v_lshlrev_b32_e32 v210, 2, v213
	v_sub_u32_e32 v158, v212, v210
	v_add_u32_e32 v158, s5, v158
	v_add_u32_e32 v159, 16, v158
	v_and_b32_e32 v209, 31, v163
	v_lshlrev_b32_e32 v209, 3, v209
	ds_read_b64 v[210:211], v209 offset:32768
	v_bfe_u32 v190, v163, 1, 3
	v_and_b32_e32 v206, 3, v190
	v_xor_b32_e32 v206, v206, v213
	v_lshlrev_b32_e32 v206, 4, v206
	v_lshrrev_b32_e32 v207, 2, v190
	v_lshl_or_b32 v206, v207, 6, v206
	v_lshl_or_b32 v132, v212, 7, v206
	v_xor_b32_e32 v133, 64, v132
	v_lshrrev_b32_e32 v206, 1, v213
	v_and_b32_e32 v207, 1, v190
	v_xor_b32_e32 v206, v206, v207
	v_and_b32_e32 v207, 6, v190
	v_or_b32_e32 v206, v206, v207
	v_lshlrev_b32_e32 v206, 4, v206
	v_and_b32_e32 v207, 1, v213
	v_lshl_or_b32 v206, v207, 3, v206
	v_lshl_or_b32 v134, v212, 7, v206
	v_add_u32_e32 v134, 0x2000, v134
	v_xor_b32_e32 v135, 32, v134
	v_xor_b32_e32 v148, 64, v134
	v_xor_b32_e32 v149, 32, v148
	v_lshrrev_b32_e32 v206, 3, v163
	v_and_b32_e32 v207, 7, v163
	v_bfe_u32 v208, v163, 4, 3
	v_xor_b32_e32 v207, v207, v208
	v_lshlrev_b32_e32 v207, 4, v207
	v_lshl_add_u32 v150, v206, 7, v207
	v_add_u32_e32 v151, 0x1000, v150
	v_mul_u32_u24_e32 v152, 0x2080, v206
	v_add_u32_e32 v152, v152, v207
	v_add_u32_e32 v153, 0x41000, v152
	v_and_b32_e32 v214, 63, v163
	v_xor_b32_e32 v214, 32, v214
	v_lshlrev_b32_e32 v214, 2, v214
	s_waitcnt lgkmcnt(0)
	s_mov_b64 s[20:21], 0
	v_readlane_b32 s28, v210, 0
	v_readlane_b32 s29, v211, 0
	s_or_b64 s[20:21], s[20:21], s[28:29]
	v_readlane_b32 s28, v210, 1
	v_readlane_b32 s29, v211, 1
	s_or_b64 s[20:21], s[20:21], s[28:29]
	v_readlane_b32 s28, v210, 2
	v_readlane_b32 s29, v211, 2
	s_or_b64 s[20:21], s[20:21], s[28:29]
	v_readlane_b32 s28, v210, 3
	v_readlane_b32 s29, v211, 3
	s_or_b64 s[20:21], s[20:21], s[28:29]
	v_readlane_b32 s28, v210, 4
	v_readlane_b32 s29, v211, 4
	s_or_b64 s[20:21], s[20:21], s[28:29]
	v_readlane_b32 s28, v210, 5
	v_readlane_b32 s29, v211, 5
	s_or_b64 s[20:21], s[20:21], s[28:29]
	v_readlane_b32 s28, v210, 6
	v_readlane_b32 s29, v211, 6
	s_or_b64 s[20:21], s[20:21], s[28:29]
	v_readlane_b32 s28, v210, 7
	v_readlane_b32 s29, v211, 7
	s_or_b64 s[20:21], s[20:21], s[28:29]
	v_readlane_b32 s28, v210, 8
	v_readlane_b32 s29, v211, 8
	s_or_b64 s[20:21], s[20:21], s[28:29]
	v_readlane_b32 s28, v210, 9
	v_readlane_b32 s29, v211, 9
	s_or_b64 s[20:21], s[20:21], s[28:29]
	v_readlane_b32 s28, v210, 10
	v_readlane_b32 s29, v211, 10
	s_or_b64 s[20:21], s[20:21], s[28:29]
	v_readlane_b32 s28, v210, 11
	v_readlane_b32 s29, v211, 11
	s_or_b64 s[20:21], s[20:21], s[28:29]
	v_readlane_b32 s28, v210, 12
	v_readlane_b32 s29, v211, 12
	s_or_b64 s[20:21], s[20:21], s[28:29]
	v_readlane_b32 s28, v210, 13
	v_readlane_b32 s29, v211, 13
	s_or_b64 s[20:21], s[20:21], s[28:29]
	v_readlane_b32 s28, v210, 14
	v_readlane_b32 s29, v211, 14
	s_or_b64 s[20:21], s[20:21], s[28:29]
	v_readlane_b32 s28, v210, 15
	v_readlane_b32 s29, v211, 15
	s_or_b64 s[20:21], s[20:21], s[28:29]
	v_readlane_b32 s28, v210, 16
	v_readlane_b32 s29, v211, 16
	s_or_b64 s[20:21], s[20:21], s[28:29]
	v_readlane_b32 s28, v210, 17
	v_readlane_b32 s29, v211, 17
	s_or_b64 s[20:21], s[20:21], s[28:29]
	v_readlane_b32 s28, v210, 18
	v_readlane_b32 s29, v211, 18
	s_or_b64 s[20:21], s[20:21], s[28:29]
	v_readlane_b32 s28, v210, 19
	v_readlane_b32 s29, v211, 19
	s_or_b64 s[20:21], s[20:21], s[28:29]
	v_readlane_b32 s28, v210, 20
	v_readlane_b32 s29, v211, 20
	s_or_b64 s[20:21], s[20:21], s[28:29]
	v_readlane_b32 s28, v210, 21
	v_readlane_b32 s29, v211, 21
	s_or_b64 s[20:21], s[20:21], s[28:29]
	v_readlane_b32 s28, v210, 22
	v_readlane_b32 s29, v211, 22
	s_or_b64 s[20:21], s[20:21], s[28:29]
	v_readlane_b32 s28, v210, 23
	v_readlane_b32 s29, v211, 23
	s_or_b64 s[20:21], s[20:21], s[28:29]
	v_readlane_b32 s28, v210, 24
	v_readlane_b32 s29, v211, 24
	s_or_b64 s[20:21], s[20:21], s[28:29]
	v_readlane_b32 s28, v210, 25
	v_readlane_b32 s29, v211, 25
	s_or_b64 s[20:21], s[20:21], s[28:29]
	v_readlane_b32 s28, v210, 26
	v_readlane_b32 s29, v211, 26
	s_or_b64 s[20:21], s[20:21], s[28:29]
	v_readlane_b32 s28, v210, 27
	v_readlane_b32 s29, v211, 27
	s_or_b64 s[20:21], s[20:21], s[28:29]
	v_readlane_b32 s28, v210, 28
	v_readlane_b32 s29, v211, 28
	s_or_b64 s[20:21], s[20:21], s[28:29]
	v_readlane_b32 s28, v210, 29
	v_readlane_b32 s29, v211, 29
	s_or_b64 s[20:21], s[20:21], s[28:29]
	v_readlane_b32 s28, v210, 30
	v_readlane_b32 s29, v211, 30
	s_or_b64 s[20:21], s[20:21], s[28:29]
	v_readlane_b32 s28, v210, 31
	v_readlane_b32 s29, v211, 31
	s_or_b64 s[20:21], s[20:21], s[28:29]
	v_readlane_b32 s10, v236, 43
	v_readlane_b32 s11, v236, 44
	s_lshl_b32 s28, s6, 19
	s_add_u32 s10, s10, s28
	s_addc_u32 s11, s11, 0
	v_readlane_b32 s12, v237, 51
	v_readlane_b32 s13, v237, 52
	s_mul_i32 s28, s6, 0x82000
	s_add_u32 s12, s12, s28
	s_addc_u32 s13, s13, 0
	s_mov_b32 s27, -1
	s_mov_b32 s26, 0
	s_waitcnt vmcnt(0)
	v_mov_b32_e32 v128, 0
	v_mov_b32_e32 v130, 0
	v_mov_b32_e32 v129, 0
	v_mov_b32_e32 v131, 0
	v_mov_b32_e32 v2, 0
	v_mov_b32_e32 v3, 0
	v_mov_b32_e32 v4, 0
	v_mov_b32_e32 v5, 0
	v_mov_b32_e32 v6, 0
	v_mov_b32_e32 v7, 0
	v_mov_b32_e32 v8, 0
	v_mov_b32_e32 v9, 0
	v_mov_b32_e32 v10, 0
	v_mov_b32_e32 v11, 0
	v_mov_b32_e32 v12, 0
	v_mov_b32_e32 v13, 0
	v_mov_b32_e32 v14, 0
	v_mov_b32_e32 v15, 0
	v_mov_b32_e32 v16, 0
	v_mov_b32_e32 v17, 0
	v_mov_b32_e32 v18, 0
	v_mov_b32_e32 v19, 0
	v_mov_b32_e32 v20, 0
	v_mov_b32_e32 v21, 0
	v_mov_b32_e32 v22, 0
	v_mov_b32_e32 v23, 0
	v_mov_b32_e32 v24, 0
	v_mov_b32_e32 v25, 0
	v_mov_b32_e32 v26, 0
	v_mov_b32_e32 v27, 0
	v_mov_b32_e32 v28, 0
	v_mov_b32_e32 v29, 0
	v_mov_b32_e32 v30, 0
	v_mov_b32_e32 v31, 0
	v_mov_b32_e32 v32, 0
	v_mov_b32_e32 v33, 0
	s_mov_b32 s24, 1
	s_ff1_i32_b64 s22, s[20:21]
	s_add_u32 s28, s20, -1
	s_addc_u32 s29, s21, -1
	s_and_b64 s[20:21], s[20:21], s[28:29]
	s_lshl_b32 s28, s22, 13
	s_add_u32 s14, s10, s28
	s_addc_u32 s15, s11, 0
	s_lshl_b32 s28, s22, 7
	s_add_u32 s16, s12, s28
	s_addc_u32 s17, s13, 0
	s_mov_b32 m0, s18
	s_nop 0
	global_load_lds_dwordx4 v150, s[14:15]
	s_add_u32 m0, s18, 0x1000
	s_nop 0
	global_load_lds_dwordx4 v151, s[14:15]
	s_add_u32 m0, s18, 0x2000
	s_nop 0
	global_load_lds_dwordx4 v152, s[16:17]
	s_add_u32 m0, s18, 0x3000
	s_nop 0
	global_load_lds_dwordx4 v153, s[16:17]
	s_waitcnt vmcnt(0)
	s_barrier
	s_branch .La2_it0
